# PEER: experts counting-sorted by table region, split U/V sweeps (L2 locality), hoisted token front-end loads; hyena ds_read_b64 pairs
# speedup vs baseline: 1.0460x; 1.0460x over previous
; __device__ __forceinline__ float bflo(unsigned w) { return __uint_as_float(w << 16); }
; __device__ __forceinline__ float bfhi(unsigned w) { return __uint_as_float(w & 0xffff0000u); }
; __device__ __forceinline__ float key2f(unsigned k) { return __uint_as_float((k & 0x80000000u) ? (k & 0x7fffffffu) : ~k); }
; __device__ void ph_peer(const float* __restrict__ SC, const bf16_t* __restrict__ H  , const float* __restrict__ gffn, const unsigned char* __restrict__ U, const unsigned char* __restrict__ V, float* X, const float* __restrict__ fgain) {
;     ...
;     for (int tok = blockIdx.x * 8 + wave; tok < GT; tok += gridDim.x * 8) {
;         float rstd;
;         {   const u32x4* hp0 = (const u32x4*)(H + (size_t)tok * 1024); float ss = 0.f;
; #pragma unroll
;             for (int s4 = 0; s4 < 2; ++s4) { const u32x4 w = hp0[s4 * 64 + lane]; const unsigned ww[4] = {w.x, w.y, w.z, w.w};
; #pragma unroll
;                 for (int e4 = 0; e4 < 4; ++e4) { const float lo = bflo(ww[e4]), hi = bfhi(ww[e4]); ss += lo * lo + hi * hi; } }
;             ss = wave_sum(ss); rstd = rsqrtf(ss * (1.0f / 1024.0f) + 1e-6f); }
;     ...
;             for (int u = 0; u < 2; ++u) {
;                 const float bs = key2f(best[u] & ~255u);
;                 const int pos = 255 - (int)(best[u] & 255u);
;                 const int e0 = __shfl(n0[u], (pos >> 4) & 15), e1 = __shfl(n1[u], pos & 15);
;                 const float mxs = __shfl(bs, 0);
;                 float e = lane < 16 ? __expf((bs - mxs) * rstd) : 0.f;
;                 const float den = row16_sum(e);
;                 const int iv = __shfl(e0 * 128 + e1, lane & 15); const float gv = __shfl(e / den, lane & 15);
;                 const int hh = h + u;
;                 if (grp == (hh & 3)) { if (hh < 4) { idx_lo = iv; g_lo = gv; } else { idx_hi = iv; g_hi = gv; } } }
.LBB0_221:
	v_ashrrev_i32_e32 v73, 31, v72
	v_readlane_b32 s0, v253, 24
	v_lshlrev_b64 v[0:1], 11, v[72:73]
	v_readlane_b32 s1, v253, 25
	v_lshlrev_b64 v[96:97], 10, v[72:73]
	v_mov_b32_e32 v156, 0
	v_lshl_add_u64 v[0:1], s[0:1], 0, v[0:1]
	v_lshl_add_u64 v[6:7], v[0:1], 0, v[128:129]
	global_load_dwordx4 v[2:5], v[6:7], off
	global_load_dwordx4 v[122:125], v[6:7], off offset:1024
	v_mov_b32_e32 v95, v129
	v_lshl_add_u64 v[216:217], v[0:1], 0, v[94:95]
	global_load_dwordx4 v[180:183], v[216:217], off offset:0
	global_load_dwordx4 v[184:187], v[216:217], off offset:16
	global_load_dwordx4 v[188:191], v[216:217], off offset:32
	global_load_dwordx4 v[192:195], v[216:217], off offset:48
	global_load_dwordx4 v[196:199], v[216:217], off offset:64
	global_load_dwordx4 v[200:203], v[216:217], off offset:80
	global_load_dwordx4 v[204:207], v[216:217], off offset:96
	global_load_dwordx4 v[208:211], v[216:217], off offset:112
	global_load_dwordx4 v[32:35], v[78:79], off offset:32
	global_load_dwordx4 v[36:39], v[78:79], off offset:48
	global_load_dwordx4 v[40:43], v[78:79], off offset:64
	global_load_dwordx4 v[44:47], v[78:79], off offset:80
	global_load_dwordx4 v[48:51], v[78:79], off offset:96
	global_load_dwordx4 v[52:55], v[78:79], off offset:112
	global_load_dwordx4 v[56:59], v[78:79], off offset:128
	global_load_dwordx4 v[60:63], v[78:79], off offset:144
	global_load_dwordx4 v[98:101], v[78:79], off offset:160
	global_load_dwordx4 v[102:105], v[78:79], off offset:176
	global_load_dwordx4 v[106:109], v[78:79], off offset:192
	global_load_dwordx4 v[110:113], v[78:79], off offset:208
	global_load_dwordx4 v[114:117], v[78:79], off offset:224
	global_load_dwordx4 v[118:121], v[78:79], off offset:240
	v_mov_b32_e32 v157, 0
	v_mov_b32_e32 v158, 0
	s_waitcnt vmcnt(23)
	v_lshlrev_b32_e32 v8, 16, v2
	v_and_b32_e32 v2, 0xffff0000, v2
	v_mul_f32_e32 v2, v2, v2
	v_fmac_f32_e32 v2, v8, v8
	v_lshlrev_b32_e32 v8, 16, v3
	v_and_b32_e32 v3, 0xffff0000, v3
	v_mul_f32_e32 v3, v3, v3
	v_fmac_f32_e32 v3, v8, v8
	v_add_f32_e32 v8, v2, v3
	v_lshlrev_b32_e32 v3, 16, v5
	v_lshlrev_b32_e32 v2, 16, v4
	v_and_b32_e32 v5, 0xffff0000, v5
	v_and_b32_e32 v4, 0xffff0000, v4
	v_pk_mul_f32 v[4:5], v[4:5], v[4:5]
	s_nop 0
	v_pk_fma_f32 v[2:3], v[2:3], v[2:3], v[4:5]
	s_nop 0
	v_add_f32_e32 v2, v2, v8
	v_add_f32_e32 v8, v3, v2
	s_waitcnt vmcnt(22)
	v_mov_b32_e32 v2, v122
	v_mov_b32_e32 v3, v123
	v_mov_b32_e32 v4, v124
	v_mov_b32_e32 v5, v125
	v_lshlrev_b32_e32 v7, 16, v3
	v_lshlrev_b32_e32 v6, 16, v2
	v_and_b32_e32 v3, 0xffff0000, v3
	v_and_b32_e32 v2, 0xffff0000, v2
	v_pk_mul_f32 v[2:3], v[2:3], v[2:3]
	s_nop 0
	v_pk_fma_f32 v[2:3], v[6:7], v[6:7], v[2:3]
	s_nop 0
	v_add_f32_e32 v2, v2, v8
	v_add_f32_e32 v6, v3, v2
	v_lshlrev_b32_e32 v3, 16, v5
	v_lshlrev_b32_e32 v2, 16, v4
	v_and_b32_e32 v5, 0xffff0000, v5
	v_and_b32_e32 v4, 0xffff0000, v4
	v_pk_mul_f32 v[4:5], v[4:5], v[4:5]
	s_nop 0
	v_pk_fma_f32 v[2:3], v[2:3], v[2:3], v[4:5]
	s_nop 0
	v_add_f32_e32 v2, v2, v6
	v_add_f32_e32 v2, v3, v2
	s_nop 1
	v_add_f32_dpp v2, v2, v2 quad_perm:[1,0,3,2] row_mask:0xf bank_mask:0xf bound_ctrl:1
	s_nop 1
	v_add_f32_dpp v2, v2, v2 quad_perm:[2,3,0,1] row_mask:0xf bank_mask:0xf bound_ctrl:1
	s_nop 1
	v_add_f32_dpp v2, v2, v2 row_half_mirror row_mask:0xf bank_mask:0xf bound_ctrl:1
	s_nop 1
	v_add_f32_dpp v2, v2, v2 row_mirror row_mask:0xf bank_mask:0xf bound_ctrl:1
	s_nop 0
	v_readlane_b32 s2, v2, 16
	v_readlane_b32 s6, v2, 48
	v_readlane_b32 s0, v2, 0
	v_readlane_b32 s1, v2, 32
	v_mov_b32_e32 v2, s2
	v_mov_b32_e32 v3, s6
	v_pk_add_f32 v[2:3], s[0:1], v[2:3]
	s_mov_b32 s0, 0x800000
	v_add_f32_e32 v2, v2, v3
	v_fmamk_f32 v2, v2, 0x3a800000, v170
	v_cmp_gt_f32_e32 vcc, s0, v2
	v_mul_f32_e32 v3, 0x4b800000, v2
	s_mov_b32 s6, 0
	v_cndmask_b32_e32 v2, v2, v3, vcc
	v_rsq_f32_e32 v2, v2
	s_nop 0
	v_mul_f32_e32 v3, 0x45800000, v2
	v_cndmask_b32_e32 v12, v2, v3, vcc
	v_lshlrev_b64 v[2:3], 13, v[72:73]
	v_lshl_add_u64 v[2:3], v[92:93], 0, v[2:3]
	v_mov_b32_e32 v73, 0
.Lpeer_partB:
	v_lshrrev_b32_e32 v2, 11, v72
	v_lshrrev_b32_e32 v3, 6, v131
	v_lshl_add_u32 v2, v2, 3, v91
	v_mul_u32_u24_e32 v3, 0x1c00, v3
	v_mul_u32_u24_e32 v2, 0x70, v2
	v_and_b32_e32 v4, 15, v74
	v_add_u32_e32 v3, 0x12000, v3
	v_add_u32_e32 v2, v3, v2
	v_add_u32_e32 v5, v2, v4
	v_lshl_add_u32 v6, v4, 2, v2
	ds_read_u8 v7, v5 offset:96
	ds_read_u8 v8, v5 offset:544
	ds_read_b32 v9, v6 offset:32
	ds_read_b32 v10, v6 offset:480
	ds_read_b32 v11, v2 offset:32
	ds_read_b32 v13, v2 offset:480
	s_waitcnt lgkmcnt(4)
	v_not_b32_e32 v7, v7
	v_not_b32_e32 v8, v8
	v_bfe_u32 v14, v7, 4, 4
	v_and_b32_e32 v7, 15, v7
	v_bfe_u32 v15, v8, 4, 4
	v_and_b32_e32 v8, 15, v8
	v_add_u32_e32 v14, v2, v14
	v_add_u32_e32 v7, v2, v7
	v_add_u32_e32 v15, v2, v15
	v_add_u32_e32 v8, v2, v8
	ds_read_u8 v14, v14
	ds_read_u8 v7, v7 offset:16
	ds_read_u8 v15, v15 offset:448
	ds_read_u8 v8, v8 offset:464
	s_waitcnt lgkmcnt(4)
; __device__ __forceinline__ float key2f(unsigned k) { return __uint_as_float((k & 0x80000000u) ? (k & 0x7fffffffu) : ~k); }
; __device__ void ph_peer(const float* __restrict__ SC, const bf16_t* __restrict__ H  , const float* __restrict__ gffn, const unsigned char* __restrict__ U, const unsigned char* __restrict__ V, float* X, const float* __restrict__ fgain) {
;     ...
;             for (int u = 0; u < 2; ++u) {
;                 const float bs = key2f(best[u] & ~255u);
;                 const int pos = 255 - (int)(best[u] & 255u);
;                 const int e0 = __shfl(n0[u], (pos >> 4) & 15), e1 = __shfl(n1[u], pos & 15);
;                 const float mxs = __shfl(bs, 0);
;                 float e = lane < 16 ? __expf((bs - mxs) * rstd) : 0.f;
;                 const float den = row16_sum(e);
;                 const int iv = __shfl(e0 * 128 + e1, lane & 15); const float gv = __shfl(e / den, lane & 15);
;                 const int hh = h + u;
;                 if (grp == (hh & 3)) { if (hh < 4) { idx_lo = iv; g_lo = gv; } else { idx_hi = iv; g_hi = gv; } } }
	v_sub_f32_e32 v9, v9, v11
	v_sub_f32_e32 v10, v10, v13
	v_mul_f32_e32 v9, v12, v9
	v_mul_f32_e32 v10, v12, v10
	v_mul_f32_e32 v9, 0x3fb8aa3b, v9
	v_mul_f32_e32 v10, 0x3fb8aa3b, v10
	v_exp_f32_e32 v9, v9
	v_exp_f32_e32 v10, v10
	s_nop 1
	v_add_f32_dpp v11, v9, v9 quad_perm:[1,0,3,2] row_mask:0xf bank_mask:0xf bound_ctrl:1
	v_add_f32_dpp v13, v10, v10 quad_perm:[1,0,3,2] row_mask:0xf bank_mask:0xf bound_ctrl:1
	s_nop 0
	v_add_f32_dpp v11, v11, v11 quad_perm:[2,3,0,1] row_mask:0xf bank_mask:0xf bound_ctrl:1
	v_add_f32_dpp v13, v13, v13 quad_perm:[2,3,0,1] row_mask:0xf bank_mask:0xf bound_ctrl:1
	s_nop 0
	v_add_f32_dpp v11, v11, v11 row_half_mirror row_mask:0xf bank_mask:0xf bound_ctrl:1
	v_add_f32_dpp v13, v13, v13 row_half_mirror row_mask:0xf bank_mask:0xf bound_ctrl:1
	s_nop 0
	v_add_f32_dpp v11, v11, v11 row_mirror row_mask:0xf bank_mask:0xf bound_ctrl:1
	v_add_f32_dpp v13, v13, v13 row_mirror row_mask:0xf bank_mask:0xf bound_ctrl:1
	s_nop 0
	v_div_scale_f32 v16, s[0:1], v11, v11, v9
	v_div_scale_f32 v17, s[0:1], v13, v13, v10
	v_rcp_f32_e32 v18, v16
	v_rcp_f32_e32 v19, v17
	s_nop 0
	v_fma_f32 v20, -v16, v18, 1.0
	v_fma_f32 v21, -v17, v19, 1.0
	v_fmac_f32_e32 v18, v20, v18
	v_fmac_f32_e32 v19, v21, v19
	v_div_scale_f32 v20, vcc, v9, v11, v9
	v_mul_f32_e32 v22, v20, v18
	v_fma_f32 v24, -v16, v22, v20
	v_fmac_f32_e32 v22, v24, v18
	v_fma_f32 v20, -v16, v22, v20
	v_div_fmas_f32 v20, v20, v18, v22
	v_div_fixup_f32 v73, v20, v11, v9
	v_div_scale_f32 v21, vcc, v10, v13, v10
	v_mul_f32_e32 v23, v21, v19
	v_fma_f32 v25, -v17, v23, v21
	v_fmac_f32_e32 v23, v25, v19
	v_fma_f32 v21, -v17, v23, v21
	v_div_fmas_f32 v21, v21, v19, v23
	v_div_fixup_f32 v158, v21, v13, v10
	s_waitcnt lgkmcnt(0)
	v_and_b32_e32 v14, 0x7f, v14
	v_and_b32_e32 v7, 0x7f, v7
	v_and_b32_e32 v15, 0x7f, v15
	v_and_b32_e32 v8, 0x7f, v8
	v_lshl_or_b32 v14, v14, 7, v7
	v_lshl_or_b32 v15, v15, 7, v8
	v_xor_b32_e32 v156, 0x3fff, v14
	v_xor_b32_e32 v157, 0x3fff, v15
	v_lshrrev_b32_e32 v2, 11, v156
	v_lshrrev_b32_e32 v3, 11, v157
	s_mov_b32 s2, 0
	v_mov_b32_e32 v6, 0
	v_mov_b32_e32 v7, 0
	v_cmp_eq_u32_e64 s[0:1], 0, v2
	v_cmp_eq_u32_e64 s[6:7], 0, v3
	s_nop 1
	v_mbcnt_lo_u32_b32 v4, s0, 0
	v_mbcnt_lo_u32_b32 v5, s6, 0
	v_mbcnt_hi_u32_b32 v4, s1, v4
	v_mbcnt_hi_u32_b32 v5, s7, v5
	s_bcnt1_i32_b64 s14, s[0:1]
	s_bcnt1_i32_b64 s15, s[6:7]
	v_add_u32_e32 v4, s2, v4
	s_add_i32 s14, s2, s14
	s_nop 0
	v_add_u32_e32 v5, s14, v5
	s_add_i32 s2, s14, s15
	v_cndmask_b32_e64 v6, v6, v4, s[0:1]
	v_cndmask_b32_e64 v7, v7, v5, s[6:7]
	v_cmp_eq_u32_e64 s[0:1], 1, v2
	v_cmp_eq_u32_e64 s[6:7], 1, v3
	s_nop 1
	v_mbcnt_lo_u32_b32 v4, s0, 0
	v_mbcnt_lo_u32_b32 v5, s6, 0
	v_mbcnt_hi_u32_b32 v4, s1, v4
	v_mbcnt_hi_u32_b32 v5, s7, v5
	s_bcnt1_i32_b64 s14, s[0:1]
	s_bcnt1_i32_b64 s15, s[6:7]
	v_add_u32_e32 v4, s2, v4
	s_add_i32 s14, s2, s14
	s_nop 0
	v_add_u32_e32 v5, s14, v5
	s_add_i32 s2, s14, s15
	v_cndmask_b32_e64 v6, v6, v4, s[0:1]
	v_cndmask_b32_e64 v7, v7, v5, s[6:7]
	v_cmp_eq_u32_e64 s[0:1], 2, v2
	v_cmp_eq_u32_e64 s[6:7], 2, v3
	s_nop 1
	v_mbcnt_lo_u32_b32 v4, s0, 0
	v_mbcnt_lo_u32_b32 v5, s6, 0
	v_mbcnt_hi_u32_b32 v4, s1, v4
	v_mbcnt_hi_u32_b32 v5, s7, v5
	s_bcnt1_i32_b64 s14, s[0:1]
	s_bcnt1_i32_b64 s15, s[6:7]
	v_add_u32_e32 v4, s2, v4
	s_add_i32 s14, s2, s14
	s_nop 0
	v_add_u32_e32 v5, s14, v5
	s_add_i32 s2, s14, s15
	v_cndmask_b32_e64 v6, v6, v4, s[0:1]
	v_cndmask_b32_e64 v7, v7, v5, s[6:7]
	v_cmp_eq_u32_e64 s[0:1], 3, v2
	v_cmp_eq_u32_e64 s[6:7], 3, v3
	s_nop 1
	v_mbcnt_lo_u32_b32 v4, s0, 0
	v_mbcnt_lo_u32_b32 v5, s6, 0
	v_mbcnt_hi_u32_b32 v4, s1, v4
	v_mbcnt_hi_u32_b32 v5, s7, v5
	s_bcnt1_i32_b64 s14, s[0:1]
	s_bcnt1_i32_b64 s15, s[6:7]
	v_add_u32_e32 v4, s2, v4
	s_add_i32 s14, s2, s14
	s_nop 0
	v_add_u32_e32 v5, s14, v5
	s_add_i32 s2, s14, s15
	v_cndmask_b32_e64 v6, v6, v4, s[0:1]
	v_cndmask_b32_e64 v7, v7, v5, s[6:7]
	v_cmp_eq_u32_e64 s[0:1], 4, v2
	v_cmp_eq_u32_e64 s[6:7], 4, v3
	s_nop 1
	v_mbcnt_lo_u32_b32 v4, s0, 0
	v_mbcnt_lo_u32_b32 v5, s6, 0
	v_mbcnt_hi_u32_b32 v4, s1, v4
	v_mbcnt_hi_u32_b32 v5, s7, v5
	s_bcnt1_i32_b64 s14, s[0:1]
	s_bcnt1_i32_b64 s15, s[6:7]
	v_add_u32_e32 v4, s2, v4
	s_add_i32 s14, s2, s14
	s_nop 0
	v_add_u32_e32 v5, s14, v5
	s_add_i32 s2, s14, s15
	v_cndmask_b32_e64 v6, v6, v4, s[0:1]
	v_cndmask_b32_e64 v7, v7, v5, s[6:7]
	v_cmp_eq_u32_e64 s[0:1], 5, v2
	v_cmp_eq_u32_e64 s[6:7], 5, v3
	s_nop 1
	v_mbcnt_lo_u32_b32 v4, s0, 0
	v_mbcnt_lo_u32_b32 v5, s6, 0
	v_mbcnt_hi_u32_b32 v4, s1, v4
	v_mbcnt_hi_u32_b32 v5, s7, v5
	s_bcnt1_i32_b64 s14, s[0:1]
	s_bcnt1_i32_b64 s15, s[6:7]
	v_add_u32_e32 v4, s2, v4
	s_add_i32 s14, s2, s14
	s_nop 0
	v_add_u32_e32 v5, s14, v5
	s_add_i32 s2, s14, s15
	v_cndmask_b32_e64 v6, v6, v4, s[0:1]
	v_cndmask_b32_e64 v7, v7, v5, s[6:7]
	v_cmp_eq_u32_e64 s[0:1], 6, v2
	v_cmp_eq_u32_e64 s[6:7], 6, v3
	s_nop 1
	v_mbcnt_lo_u32_b32 v4, s0, 0
	v_mbcnt_lo_u32_b32 v5, s6, 0
	v_mbcnt_hi_u32_b32 v4, s1, v4
	v_mbcnt_hi_u32_b32 v5, s7, v5
	s_bcnt1_i32_b64 s14, s[0:1]
	s_bcnt1_i32_b64 s15, s[6:7]
	v_add_u32_e32 v4, s2, v4
	s_add_i32 s14, s2, s14
	s_nop 0
	v_add_u32_e32 v5, s14, v5
	s_add_i32 s2, s14, s15
	v_cndmask_b32_e64 v6, v6, v4, s[0:1]
	v_cndmask_b32_e64 v7, v7, v5, s[6:7]
	v_cmp_eq_u32_e64 s[0:1], 7, v2
	v_cmp_eq_u32_e64 s[6:7], 7, v3
	s_nop 1
	v_mbcnt_lo_u32_b32 v4, s0, 0
	v_mbcnt_lo_u32_b32 v5, s6, 0
	v_mbcnt_hi_u32_b32 v4, s1, v4
	v_mbcnt_hi_u32_b32 v5, s7, v5
	s_bcnt1_i32_b64 s14, s[0:1]
	s_bcnt1_i32_b64 s15, s[6:7]
	v_add_u32_e32 v4, s2, v4
	s_add_i32 s14, s2, s14
	s_nop 0
	v_add_u32_e32 v5, s14, v5
	s_add_i32 s2, s14, s15
	v_cndmask_b32_e64 v6, v6, v4, s[0:1]
	v_cndmask_b32_e64 v7, v7, v5, s[6:7]
	v_lshrrev_b32_e32 v8, 6, v131
	v_mul_u32_u24_e32 v8, 0x2400, v8
	v_lshl_add_u32 v9, v6, 2, v8
	v_lshl_add_u32 v10, v7, 2, v8
	ds_write_b32 v9, v156
	ds_write_b32 v10, v157
	ds_write_b32 v9, v73 offset:512
	ds_write_b32 v10, v158 offset:512
; __device__ __forceinline__ unsigned cvt_pk_bf16(float lo, float hi) { unsigned r; asm volatile("v_cvt_pk_bf16_f32 %0, %1, %2" : "=v"(r) : "v"(lo), "v"(hi)); return r; }
; __device__ __forceinline__ float bflo(unsigned w) { return __uint_as_float(w << 16); }
; __device__ __forceinline__ float bfhi(unsigned w) { return __uint_as_float(w & 0xffff0000u); }
; __device__ void ph_peer(const float* __restrict__ SC, const bf16_t* __restrict__ H  , const float* __restrict__ gffn, const unsigned char* __restrict__ U, const unsigned char* __restrict__ V, float* X, const float* __restrict__ fgain) {
;     ...
;         unsigned hf2[32];
;         {   const u32x4* hp = (const u32x4*)(H + (size_t)tok * 1024 + 64 * sub);
; #pragma unroll
;             for (int q = 0; q < 8; ++q) { const u32x4 w = hp[q];
;                 const float4 ga = *(const float4*)(gffn + 64 * sub + q * 8), gb = *(const float4*)(gffn + 64 * sub + q * 8 + 4);
;                 hf2[q * 4 + 0] = cvt_pk_bf16(bflo(w.x) * rstd * ga.x, bfhi(w.x) * rstd * ga.y);
;                 hf2[q * 4 + 1] = cvt_pk_bf16(bflo(w.y) * rstd * ga.z, bfhi(w.y) * rstd * ga.w);
;                 hf2[q * 4 + 2] = cvt_pk_bf16(bflo(w.z) * rstd * gb.x, bfhi(w.z) * rstd * gb.y);
;                 hf2[q * 4 + 3] = cvt_pk_bf16(bflo(w.w) * rstd * gb.z, bfhi(w.w) * rstd * gb.w); } }
.LBB0_230:
	s_waitcnt vmcnt(0) lgkmcnt(0)
	v_lshlrev_b32_e32 v2, 16, v180
	v_and_b32_e32 v3, 0xffff0000, v180
	v_mul_f32_e32 v2, v12, v2
	v_mul_f32_e32 v3, v12, v3
	v_mul_f32_e32 v2, v64, v2
	v_mul_f32_e32 v3, v65, v3
	v_cvt_pk_bf16_f32 v95, v2, v3
	v_lshlrev_b32_e32 v2, 16, v181
	v_and_b32_e32 v3, 0xffff0000, v181
	v_mul_f32_e32 v2, v12, v2
	v_mul_f32_e32 v3, v12, v3
	v_mul_f32_e32 v2, v66, v2
	v_mul_f32_e32 v3, v67, v3
	v_cvt_pk_bf16_f32 v159, v2, v3
	v_lshlrev_b32_e32 v2, 16, v182
	v_and_b32_e32 v3, 0xffff0000, v182
	v_mul_f32_e32 v2, v12, v2
	v_mul_f32_e32 v3, v12, v3
	v_mul_f32_e32 v2, v68, v2
	v_mul_f32_e32 v3, v69, v3
	v_cvt_pk_bf16_f32 v160, v2, v3
	v_lshlrev_b32_e32 v2, 16, v183
	v_and_b32_e32 v3, 0xffff0000, v183
	v_mul_f32_e32 v2, v12, v2
	v_mul_f32_e32 v3, v12, v3
	v_mul_f32_e32 v2, v70, v2
	v_mul_f32_e32 v3, v71, v3
	v_cvt_pk_bf16_f32 v161, v2, v3
	v_lshlrev_b32_e32 v2, 16, v184
	v_and_b32_e32 v3, 0xffff0000, v184
	v_mul_f32_e32 v2, v12, v2
	v_mul_f32_e32 v3, v12, v3
	v_mul_f32_e32 v2, v32, v2
	v_mul_f32_e32 v3, v33, v3
	v_cvt_pk_bf16_f32 v180, v2, v3
	v_lshlrev_b32_e32 v2, 16, v185
	v_and_b32_e32 v3, 0xffff0000, v185
	v_mul_f32_e32 v2, v12, v2
	v_mul_f32_e32 v3, v12, v3
	v_mul_f32_e32 v2, v34, v2
	v_mul_f32_e32 v3, v35, v3
	v_cvt_pk_bf16_f32 v181, v2, v3
	v_lshlrev_b32_e32 v2, 16, v186
	v_and_b32_e32 v3, 0xffff0000, v186
	v_mul_f32_e32 v2, v12, v2
	v_mul_f32_e32 v3, v12, v3
	v_mul_f32_e32 v2, v36, v2
	v_mul_f32_e32 v3, v37, v3
	v_cvt_pk_bf16_f32 v182, v2, v3
	v_lshlrev_b32_e32 v2, 16, v187
	v_and_b32_e32 v3, 0xffff0000, v187
	v_mul_f32_e32 v2, v12, v2
	v_mul_f32_e32 v3, v12, v3
	v_mul_f32_e32 v2, v38, v2
	v_mul_f32_e32 v3, v39, v3
	v_cvt_pk_bf16_f32 v183, v2, v3
	v_lshlrev_b32_e32 v2, 16, v188
	v_and_b32_e32 v3, 0xffff0000, v188
	v_mul_f32_e32 v2, v12, v2
	v_mul_f32_e32 v3, v12, v3
	v_mul_f32_e32 v2, v40, v2
	v_mul_f32_e32 v3, v41, v3
	v_cvt_pk_bf16_f32 v184, v2, v3
	v_lshlrev_b32_e32 v2, 16, v189
	v_and_b32_e32 v3, 0xffff0000, v189
	v_mul_f32_e32 v2, v12, v2
	v_mul_f32_e32 v3, v12, v3
	v_mul_f32_e32 v2, v42, v2
	v_mul_f32_e32 v3, v43, v3
	v_cvt_pk_bf16_f32 v185, v2, v3
	v_lshlrev_b32_e32 v2, 16, v190
	v_and_b32_e32 v3, 0xffff0000, v190
	v_mul_f32_e32 v2, v12, v2
	v_mul_f32_e32 v3, v12, v3
	v_mul_f32_e32 v2, v44, v2
	v_mul_f32_e32 v3, v45, v3
	v_cvt_pk_bf16_f32 v186, v2, v3
	v_lshlrev_b32_e32 v2, 16, v191
	v_and_b32_e32 v3, 0xffff0000, v191
	v_mul_f32_e32 v2, v12, v2
	v_mul_f32_e32 v3, v12, v3
	v_mul_f32_e32 v2, v46, v2
	v_mul_f32_e32 v3, v47, v3
	v_cvt_pk_bf16_f32 v187, v2, v3
	v_lshlrev_b32_e32 v2, 16, v192
	v_and_b32_e32 v3, 0xffff0000, v192
	v_mul_f32_e32 v2, v12, v2
	v_mul_f32_e32 v3, v12, v3
	v_mul_f32_e32 v2, v48, v2
	v_mul_f32_e32 v3, v49, v3
	v_cvt_pk_bf16_f32 v188, v2, v3
	v_lshlrev_b32_e32 v2, 16, v193
	v_and_b32_e32 v3, 0xffff0000, v193
	v_mul_f32_e32 v2, v12, v2
	v_mul_f32_e32 v3, v12, v3
	v_mul_f32_e32 v2, v50, v2
	v_mul_f32_e32 v3, v51, v3
	v_cvt_pk_bf16_f32 v189, v2, v3
	v_lshlrev_b32_e32 v2, 16, v194
	v_and_b32_e32 v3, 0xffff0000, v194
	v_mul_f32_e32 v2, v12, v2
	v_mul_f32_e32 v3, v12, v3
	v_mul_f32_e32 v2, v52, v2
	v_mul_f32_e32 v3, v53, v3
	v_cvt_pk_bf16_f32 v190, v2, v3
	v_lshlrev_b32_e32 v2, 16, v195
	v_and_b32_e32 v3, 0xffff0000, v195
	v_mul_f32_e32 v2, v12, v2
	v_mul_f32_e32 v3, v12, v3
	v_mul_f32_e32 v2, v54, v2
	v_mul_f32_e32 v3, v55, v3
	v_cvt_pk_bf16_f32 v191, v2, v3
	v_lshlrev_b32_e32 v2, 16, v196
	v_and_b32_e32 v3, 0xffff0000, v196
	v_mul_f32_e32 v2, v12, v2
	v_mul_f32_e32 v3, v12, v3
	v_mul_f32_e32 v2, v56, v2
	v_mul_f32_e32 v3, v57, v3
	v_cvt_pk_bf16_f32 v192, v2, v3
	v_lshlrev_b32_e32 v2, 16, v197
	v_and_b32_e32 v3, 0xffff0000, v197
	v_mul_f32_e32 v2, v12, v2
	v_mul_f32_e32 v3, v12, v3
	v_mul_f32_e32 v2, v58, v2
	v_mul_f32_e32 v3, v59, v3
	v_cvt_pk_bf16_f32 v193, v2, v3
	v_lshlrev_b32_e32 v2, 16, v198
	v_and_b32_e32 v3, 0xffff0000, v198
	v_mul_f32_e32 v2, v12, v2
	v_mul_f32_e32 v3, v12, v3
	v_mul_f32_e32 v2, v60, v2
	v_mul_f32_e32 v3, v61, v3
	v_cvt_pk_bf16_f32 v194, v2, v3
	v_lshlrev_b32_e32 v2, 16, v199
	v_and_b32_e32 v3, 0xffff0000, v199
	v_mul_f32_e32 v2, v12, v2
	v_mul_f32_e32 v3, v12, v3
	v_mul_f32_e32 v2, v62, v2
	v_mul_f32_e32 v3, v63, v3
	v_cvt_pk_bf16_f32 v195, v2, v3
	v_lshlrev_b32_e32 v2, 16, v200
	v_and_b32_e32 v3, 0xffff0000, v200
	v_mul_f32_e32 v2, v12, v2
	v_mul_f32_e32 v3, v12, v3
	v_mul_f32_e32 v2, v98, v2
	v_mul_f32_e32 v3, v99, v3
	v_cvt_pk_bf16_f32 v196, v2, v3
	v_lshlrev_b32_e32 v2, 16, v201
	v_and_b32_e32 v3, 0xffff0000, v201
	v_mul_f32_e32 v2, v12, v2
	v_mul_f32_e32 v3, v12, v3
	v_mul_f32_e32 v2, v100, v2
	v_mul_f32_e32 v3, v101, v3
	v_cvt_pk_bf16_f32 v197, v2, v3
	v_lshlrev_b32_e32 v2, 16, v202
	v_and_b32_e32 v3, 0xffff0000, v202
	v_mul_f32_e32 v2, v12, v2
	v_mul_f32_e32 v3, v12, v3
	v_mul_f32_e32 v2, v102, v2
	v_mul_f32_e32 v3, v103, v3
	v_cvt_pk_bf16_f32 v198, v2, v3
	v_lshlrev_b32_e32 v2, 16, v203
	v_and_b32_e32 v3, 0xffff0000, v203
	v_mul_f32_e32 v2, v12, v2
	v_mul_f32_e32 v3, v12, v3
	v_mul_f32_e32 v2, v104, v2
	v_mul_f32_e32 v3, v105, v3
	v_cvt_pk_bf16_f32 v199, v2, v3
	v_lshlrev_b32_e32 v2, 16, v204
	v_and_b32_e32 v3, 0xffff0000, v204
	v_mul_f32_e32 v2, v12, v2
	v_mul_f32_e32 v3, v12, v3
	v_mul_f32_e32 v2, v106, v2
	v_mul_f32_e32 v3, v107, v3
	v_cvt_pk_bf16_f32 v200, v2, v3
	v_lshlrev_b32_e32 v2, 16, v205
	v_and_b32_e32 v3, 0xffff0000, v205
	v_mul_f32_e32 v2, v12, v2
	v_mul_f32_e32 v3, v12, v3
	v_mul_f32_e32 v2, v108, v2
	v_mul_f32_e32 v3, v109, v3
	v_cvt_pk_bf16_f32 v201, v2, v3
	v_lshlrev_b32_e32 v2, 16, v206
	v_and_b32_e32 v3, 0xffff0000, v206
	v_mul_f32_e32 v2, v12, v2
	v_mul_f32_e32 v3, v12, v3
	v_mul_f32_e32 v2, v110, v2
	v_mul_f32_e32 v3, v111, v3
; __device__ void ph_peer(const float* __restrict__ SC, const bf16_t* __restrict__ H  , const float* __restrict__ gffn, const unsigned char* __restrict__ U, const unsigned char* __restrict__ V, float* X, const float* __restrict__ fgain) {
;     ...
;                 hf2[q * 4 + 3] = cvt_pk_bf16(bflo(w.w) * rstd * gb.z, bfhi(w.w) * rstd * gb.w); } }
;         const int half = lane >> 5, c32 = lane & 31;
;         float acc[32];
; #pragma unroll
;         for (int i = 0; i < 32; ++i) acc[i] = 0.f;
;         __builtin_amdgcn_s_setprio(1);
; #pragma unroll 1
;         for (int it = 0; it < 32; ++it) {
;             const int src = (it * 4 + grp) & 63;
;             const int e = __shfl(it < 16 ? idx_lo : idx_hi, src);
;             const float gt = __shfl(it < 16 ? g_lo : g_hi, src);
;             const u32x4* up = (const u32x4*)(U + (size_t)e * 768 + 48 * sub);
;             const u32x4 u0 = up[0], u1 = up[1], u2 = up[2];
;             u32x2 vw[2][3];
; #pragma unroll
;             for (int r = 0; r < 2; ++r) { const int ea = __builtin_amdgcn_readlane(e, 32 * r), eb = __builtin_amdgcn_readlane(e, 32 * r + 16);
;                 const u32x2* vp = (const u32x2*)(V + (size_t)(half ? eb : ea) * 768 + 24 * c32); vw[r][0] = vp[0]; vw[r][1] = vp[1]; vw[r][2] = vp[2]; }
;             float d0 = 0.f, d1 = 0.f, d2 = 0.f, d3 = 0.f;
;             {   const v6u_t p0 = (v6u_t){u0.x, u0.y, u0.z, u0.w, u1.x, u1.y};
;                 const v32bf_t r0 = __builtin_amdgcn_cvt_scalef32_pk32_bf16_fp6(p0, 1.0f);
; #pragma unroll
;                 for (int k = 0; k < 16; k += 4) { d0 = dot2pb(r0[2 * k], r0[2 * k + 1], hf2[k], d0); d1 = dot2pb(r0[2 * k + 2], r0[2 * k + 3], hf2[k + 1], d1);
;                     d2 = dot2pb(r0[2 * k + 4], r0[2 * k + 5], hf2[k + 2], d2); d3 = dot2pb(r0[2 * k + 6], r0[2 * k + 7], hf2[k + 3], d3); } }
;             {   const v6u_t p1 = (v6u_t){u1.z, u1.w, u2.x, u2.y, u2.z, u2.w};
;                 const v32bf_t r1 = __builtin_amdgcn_cvt_scalef32_pk32_bf16_fp6(p1, 1.0f);
; #pragma unroll
;                 for (int k = 0; k < 16; k += 4) { d0 = dot2pb(r1[2 * k], r1[2 * k + 1], hf2[16 + k], d0); d1 = dot2pb(r1[2 * k + 2], r1[2 * k + 3], hf2[16 + k + 1], d1);
;                     d2 = dot2pb(r1[2 * k + 4], r1[2 * k + 5], hf2[16 + k + 2], d2); d3 = dot2pb(r1[2 * k + 6], r1[2 * k + 7], hf2[16 + k + 3], d3); } }
	v_cvt_pk_bf16_f32 v202, v2, v3
	v_lshlrev_b32_e32 v2, 16, v207
	v_and_b32_e32 v3, 0xffff0000, v207
	v_mul_f32_e32 v2, v12, v2
	v_mul_f32_e32 v3, v12, v3
	v_mul_f32_e32 v2, v112, v2
	v_mul_f32_e32 v3, v113, v3
	v_cvt_pk_bf16_f32 v203, v2, v3
	v_lshlrev_b32_e32 v2, 16, v208
	v_and_b32_e32 v3, 0xffff0000, v208
	v_mul_f32_e32 v2, v12, v2
	v_mul_f32_e32 v3, v12, v3
	v_mul_f32_e32 v2, v114, v2
	v_mul_f32_e32 v3, v115, v3
	v_cvt_pk_bf16_f32 v204, v2, v3
	v_lshlrev_b32_e32 v2, 16, v209
	v_and_b32_e32 v3, 0xffff0000, v209
	v_mul_f32_e32 v2, v12, v2
	v_mul_f32_e32 v3, v12, v3
	v_mul_f32_e32 v2, v116, v2
	v_mul_f32_e32 v3, v117, v3
	v_cvt_pk_bf16_f32 v205, v2, v3
	v_lshlrev_b32_e32 v2, 16, v210
	v_and_b32_e32 v3, 0xffff0000, v210
	v_mul_f32_e32 v2, v12, v2
	v_mul_f32_e32 v3, v12, v3
	v_mul_f32_e32 v2, v118, v2
	v_mul_f32_e32 v3, v119, v3
	v_cvt_pk_bf16_f32 v206, v2, v3
	v_lshlrev_b32_e32 v2, 16, v211
	v_and_b32_e32 v3, 0xffff0000, v211
	v_mul_f32_e32 v2, v12, v2
	v_mul_f32_e32 v3, v12, v3
	v_mul_f32_e32 v2, v120, v2
	v_mul_f32_e32 v3, v121, v3
	v_cvt_pk_bf16_f32 v207, v2, v3
	s_setprio 1
	v_mov_b32_e32 v126, 0
	s_mov_b32 s0, 0
	s_mov_b32 s1, 0
	v_mov_b32_e32 v127, v126
	v_mov_b32_e32 v144, v126
	v_mov_b32_e32 v145, v126
	v_mov_b32_e32 v122, v126
	v_mov_b32_e32 v123, v126
	v_mov_b32_e32 v124, v126
	v_mov_b32_e32 v125, v126
	v_mov_b32_e32 v114, v126
	v_mov_b32_e32 v115, v126
	v_mov_b32_e32 v118, v126
	v_mov_b32_e32 v119, v126
	v_mov_b32_e32 v116, v126
	v_mov_b32_e32 v117, v126
	v_mov_b32_e32 v120, v126
	v_mov_b32_e32 v121, v126
	v_mov_b32_e32 v106, v126
	v_mov_b32_e32 v107, v126
	v_mov_b32_e32 v110, v126
	v_mov_b32_e32 v111, v126
	v_mov_b32_e32 v108, v126
	v_mov_b32_e32 v109, v126
	v_mov_b32_e32 v112, v126
	v_mov_b32_e32 v113, v126
	v_mov_b32_e32 v98, v126
	v_mov_b32_e32 v99, v126
	v_mov_b32_e32 v102, v126
	v_mov_b32_e32 v103, v126
	v_mov_b32_e32 v100, v126
	v_mov_b32_e32 v101, v126
	v_mov_b32_e32 v104, v126
	v_mov_b32_e32 v105, v126
	s_movk_i32 s14, 0x300
	s_mov_b32 s16, 0x3e6d3388
	s_mov_b32 s24, 0x3f07dc22
	s_mov_b32 s28, 0x3f35f0e3
	s_mov_b32 s30, 0xbe11a98e
	s_mov_b32 s36, 0x3e027906
	v_lshrrev_b32_e32 v61, 6, v131
	v_mul_u32_u24_e32 v61, 0x2400, v61
	v_lshl_add_u32 v61, v91, 2, v61
	s_mov_b32 s1, 0
	ds_read_b32 v56, v61
	ds_read_b32 v57, v61 offset:512
	v_add_u32_e32 v61, 16, v61
	s_add_i32 s1, s1, 1
	s_waitcnt lgkmcnt(1)
	v_mad_i64_i32 v[0:1], s[6:7], v56, s14, v[80:81]
	global_load_dwordx4 v[32:35], v[0:1], off
	global_load_dwordx4 v[36:39], v[0:1], off offset:16
	global_load_dwordx4 v[40:43], v[0:1], off offset:32
.Lpeer_uloop:
	ds_read_b32 v58, v61
	ds_read_b32 v59, v61 offset:512
	v_add_u32_e32 v61, 16, v61
	s_add_i32 s1, s1, 1
	s_waitcnt lgkmcnt(1)
	v_mad_i64_i32 v[0:1], s[6:7], v58, s14, v[80:81]
	global_load_dwordx4 v[218:221], v[0:1], off
	global_load_dwordx4 v[222:225], v[0:1], off offset:16
	global_load_dwordx4 v[226:229], v[0:1], off offset:32
	s_waitcnt vmcnt(4)
	v_cvt_scalef32_pk32_bf16_fp6 v[0:15], v[32:37], 1.0
	v_mov_b32_e32 v23, 0
	v_mov_b32_e32 v25, 0
	v_mov_b32_e32 v22, 0
	v_mov_b32_e32 v24, 0
	v_dot2c_f32_bf16_e32 v23, v0, v95
	v_dot2c_f32_bf16_e32 v25, v1, v159
	v_dot2c_f32_bf16_e32 v22, v2, v160
	v_dot2c_f32_bf16_e32 v24, v3, v161
	v_dot2c_f32_bf16_e32 v23, v4, v180
	v_dot2c_f32_bf16_e32 v25, v5, v181
	v_dot2c_f32_bf16_e32 v22, v6, v182
	v_dot2c_f32_bf16_e32 v24, v7, v183
	v_dot2c_f32_bf16_e32 v23, v8, v184
	v_dot2c_f32_bf16_e32 v25, v9, v185
	v_dot2c_f32_bf16_e32 v22, v10, v186
	v_dot2c_f32_bf16_e32 v24, v11, v187
	v_dot2c_f32_bf16_e32 v23, v12, v188
	v_dot2c_f32_bf16_e32 v25, v13, v189
	v_dot2c_f32_bf16_e32 v22, v14, v190
	v_dot2c_f32_bf16_e32 v24, v15, v191
	s_waitcnt vmcnt(3)
	v_cvt_scalef32_pk32_bf16_fp6 v[0:15], v[38:43], 1.0
	v_dot2c_f32_bf16_e32 v23, v0, v192
	v_dot2c_f32_bf16_e32 v25, v1, v193
	v_dot2c_f32_bf16_e32 v22, v2, v194
	v_dot2c_f32_bf16_e32 v24, v3, v195
	v_dot2c_f32_bf16_e32 v23, v4, v196
	v_dot2c_f32_bf16_e32 v25, v5, v197
	v_dot2c_f32_bf16_e32 v22, v6, v198
	v_dot2c_f32_bf16_e32 v24, v7, v199
	v_dot2c_f32_bf16_e32 v23, v8, v200
	v_dot2c_f32_bf16_e32 v25, v9, v201
	v_dot2c_f32_bf16_e32 v22, v10, v202
	v_dot2c_f32_bf16_e32 v24, v11, v203
	v_dot2c_f32_bf16_e32 v23, v12, v204
	v_dot2c_f32_bf16_e32 v25, v13, v205
	v_dot2c_f32_bf16_e32 v22, v14, v206
	v_dot2c_f32_bf16_e32 v24, v15, v207
	s_nop 2
	v_pk_add_f32 v[0:1], v[24:25], v[22:23]
	s_nop 0
	v_add_f32_e32 v0, v0, v1
	s_nop 1
	v_add_f32_dpp v0, v0, v0 quad_perm:[1,0,3,2] row_mask:0xf bank_mask:0xf bound_ctrl:1
	s_nop 1
	v_add_f32_dpp v0, v0, v0 quad_perm:[2,3,0,1] row_mask:0xf bank_mask:0xf bound_ctrl:1
	s_nop 1
	v_add_f32_dpp v0, v0, v0 row_half_mirror row_mask:0xf bank_mask:0xf bound_ctrl:1
	s_nop 1
	v_add_f32_dpp v0, v0, v0 row_mirror row_mask:0xf bank_mask:0xf bound_ctrl:1
	v_mul_f32_e32 v0, 0x3caaaaab, v0
	v_and_b32_e32 v2, 0x7fffffff, v0
	v_pk_fma_f32 v[2:3], v[2:3], s[16:17], 1.0 op_sel_hi:[0,0,0]
	v_rcp_f32_e32 v2, v2
	v_rcp_f32_e32 v3, v3
	v_mul_f32_e32 v1, v0, v0
	v_mul_f32_e32 v1, 0xbf38aa3b, v1
	v_cmp_gt_f32_e32 vcc, 0, v0
	v_pk_fma_f32 v[4:5], v[2:3], s[24:25], v[130:131] op_sel_hi:[1,0,0]
	s_nop 0
	v_pk_fma_f32 v[4:5], v[2:3], v[4:5], s[28:29] op_sel_hi:[1,1,0]
	s_nop 0
	v_pk_fma_f32 v[4:5], v[2:3], v[4:5], s[30:31] op_sel_hi:[1,1,0]
	s_nop 0
	v_pk_fma_f32 v[4:5], v[2:3], v[4:5], s[36:37] op_sel_hi:[1,1,0]
	s_nop 0
	v_pk_mul_f32 v[2:3], v[2:3], v[4:5]
	v_exp_f32_e32 v4, v1
	s_nop 0
	v_pk_mul_f32 v[2:3], v[4:5], v[2:3] op_sel_hi:[0,1]
	v_pk_fma_f32 v[4:5], v[0:1], v[2:3], v[0:1] op_sel_hi:[0,1,1] neg_lo:[1,0,0] neg_hi:[1,0,0]
	v_mul_f32_e32 v0, v0, v2
	v_cndmask_b32_e32 v0, v4, v0, vcc
	s_waitcnt lgkmcnt(0)
; __device__ __forceinline__ float gelu1(float v) { const f32x2 r = gelu_pk((f32x2){v, v}); return r.x; }
; __device__ void ph_peer(const float* __restrict__ SC, const bf16_t* __restrict__ H  , const float* __restrict__ gffn, const unsigned char* __restrict__ U, const unsigned char* __restrict__ V, float* X, const float* __restrict__ fgain) {
;     ...
;         for (int it = 0; it < 32; ++it) {
;             const int src = (it * 4 + grp) & 63;
;             const int e = __shfl(it < 16 ? idx_lo : idx_hi, src);
;             const float gt = __shfl(it < 16 ? g_lo : g_hi, src);
;             const u32x4* up = (const u32x4*)(U + (size_t)e * 768 + 48 * sub);
;             const u32x4 u0 = up[0], u1 = up[1], u2 = up[2];
;             u32x2 vw[2][3];
; #pragma unroll
;             for (int r = 0; r < 2; ++r) { const int ea = __builtin_amdgcn_readlane(e, 32 * r), eb = __builtin_amdgcn_readlane(e, 32 * r + 16);
;                 const u32x2* vp = (const u32x2*)(V + (size_t)(half ? eb : ea) * 768 + 24 * c32); vw[r][0] = vp[0]; vw[r][1] = vp[1]; vw[r][2] = vp[2]; }
;             float d0 = 0.f, d1 = 0.f, d2 = 0.f, d3 = 0.f;
;             {   const v6u_t p0 = (v6u_t){u0.x, u0.y, u0.z, u0.w, u1.x, u1.y};
;                 const v32bf_t r0 = __builtin_amdgcn_cvt_scalef32_pk32_bf16_fp6(p0, 1.0f);
; #pragma unroll
;                 for (int k = 0; k < 16; k += 4) { d0 = dot2pb(r0[2 * k], r0[2 * k + 1], hf2[k], d0); d1 = dot2pb(r0[2 * k + 2], r0[2 * k + 3], hf2[k + 1], d1);
;                     d2 = dot2pb(r0[2 * k + 4], r0[2 * k + 5], hf2[k + 2], d2); d3 = dot2pb(r0[2 * k + 6], r0[2 * k + 7], hf2[k + 3], d3); } }
;             {   const v6u_t p1 = (v6u_t){u1.z, u1.w, u2.x, u2.y, u2.z, u2.w};
;                 const v32bf_t r1 = __builtin_amdgcn_cvt_scalef32_pk32_bf16_fp6(p1, 1.0f);
; #pragma unroll
;                 for (int k = 0; k < 16; k += 4) { d0 = dot2pb(r1[2 * k], r1[2 * k + 1], hf2[16 + k], d0); d1 = dot2pb(r1[2 * k + 2], r1[2 * k + 3], hf2[16 + k + 1], d1);
;                     d2 = dot2pb(r1[2 * k + 4], r1[2 * k + 5], hf2[16 + k + 2], d2); d3 = dot2pb(r1[2 * k + 6], r1[2 * k + 7], hf2[16 + k + 3], d3); } }
;             const float d = row16_sum((d0 + d1) + (d2 + d3)) * FP6_INV;
;             const float a = gt * gelu1(d) * FP6_INV;
	v_mul_f32_e32 v0, v0, v57
	v_mul_f32_e32 v60, 0x3caaaaab, v0
	ds_write_b32 v61, v60 offset:992
	ds_read_b32 v56, v61
	ds_read_b32 v57, v61 offset:512
	v_add_u32_e32 v61, 16, v61
	s_add_i32 s1, s1, 1
	s_waitcnt lgkmcnt(1)
	v_mad_i64_i32 v[0:1], s[6:7], v56, s14, v[80:81]
	global_load_dwordx4 v[32:35], v[0:1], off
	global_load_dwordx4 v[36:39], v[0:1], off offset:16
	global_load_dwordx4 v[40:43], v[0:1], off offset:32
	s_waitcnt vmcnt(4)
	v_cvt_scalef32_pk32_bf16_fp6 v[0:15], v[218:223], 1.0
	v_mov_b32_e32 v23, 0
	v_mov_b32_e32 v25, 0
	v_mov_b32_e32 v22, 0
	v_mov_b32_e32 v24, 0
	v_dot2c_f32_bf16_e32 v23, v0, v95
	v_dot2c_f32_bf16_e32 v25, v1, v159
	v_dot2c_f32_bf16_e32 v22, v2, v160
	v_dot2c_f32_bf16_e32 v24, v3, v161
	v_dot2c_f32_bf16_e32 v23, v4, v180
	v_dot2c_f32_bf16_e32 v25, v5, v181
	v_dot2c_f32_bf16_e32 v22, v6, v182
	v_dot2c_f32_bf16_e32 v24, v7, v183
	v_dot2c_f32_bf16_e32 v23, v8, v184
	v_dot2c_f32_bf16_e32 v25, v9, v185
	v_dot2c_f32_bf16_e32 v22, v10, v186
	v_dot2c_f32_bf16_e32 v24, v11, v187
	v_dot2c_f32_bf16_e32 v23, v12, v188
	v_dot2c_f32_bf16_e32 v25, v13, v189
	v_dot2c_f32_bf16_e32 v22, v14, v190
	v_dot2c_f32_bf16_e32 v24, v15, v191
	s_waitcnt vmcnt(3)
	v_cvt_scalef32_pk32_bf16_fp6 v[0:15], v[224:229], 1.0
	v_dot2c_f32_bf16_e32 v23, v0, v192
	v_dot2c_f32_bf16_e32 v25, v1, v193
	v_dot2c_f32_bf16_e32 v22, v2, v194
	v_dot2c_f32_bf16_e32 v24, v3, v195
	v_dot2c_f32_bf16_e32 v23, v4, v196
	v_dot2c_f32_bf16_e32 v25, v5, v197
	v_dot2c_f32_bf16_e32 v22, v6, v198
	v_dot2c_f32_bf16_e32 v24, v7, v199
	v_dot2c_f32_bf16_e32 v23, v8, v200
	v_dot2c_f32_bf16_e32 v25, v9, v201
	v_dot2c_f32_bf16_e32 v22, v10, v202
	v_dot2c_f32_bf16_e32 v24, v11, v203
	v_dot2c_f32_bf16_e32 v23, v12, v204
	v_dot2c_f32_bf16_e32 v25, v13, v205
	v_dot2c_f32_bf16_e32 v22, v14, v206
	v_dot2c_f32_bf16_e32 v24, v15, v207
	s_nop 2
	v_pk_add_f32 v[0:1], v[24:25], v[22:23]
	s_nop 0
	v_add_f32_e32 v0, v0, v1
	s_nop 1
	v_add_f32_dpp v0, v0, v0 quad_perm:[1,0,3,2] row_mask:0xf bank_mask:0xf bound_ctrl:1
	s_nop 1
	v_add_f32_dpp v0, v0, v0 quad_perm:[2,3,0,1] row_mask:0xf bank_mask:0xf bound_ctrl:1
	s_nop 1
	v_add_f32_dpp v0, v0, v0 row_half_mirror row_mask:0xf bank_mask:0xf bound_ctrl:1
	s_nop 1
	v_add_f32_dpp v0, v0, v0 row_mirror row_mask:0xf bank_mask:0xf bound_ctrl:1
	v_mul_f32_e32 v0, 0x3caaaaab, v0
	v_and_b32_e32 v2, 0x7fffffff, v0
	v_pk_fma_f32 v[2:3], v[2:3], s[16:17], 1.0 op_sel_hi:[0,0,0]
	v_rcp_f32_e32 v2, v2
	v_rcp_f32_e32 v3, v3
	v_mul_f32_e32 v1, v0, v0
	v_mul_f32_e32 v1, 0xbf38aa3b, v1
	v_cmp_gt_f32_e32 vcc, 0, v0
	v_pk_fma_f32 v[4:5], v[2:3], s[24:25], v[130:131] op_sel_hi:[1,0,0]
	s_nop 0
	v_pk_fma_f32 v[4:5], v[2:3], v[4:5], s[28:29] op_sel_hi:[1,1,0]
	s_nop 0
	v_pk_fma_f32 v[4:5], v[2:3], v[4:5], s[30:31] op_sel_hi:[1,1,0]
	s_nop 0
	v_pk_fma_f32 v[4:5], v[2:3], v[4:5], s[36:37] op_sel_hi:[1,1,0]
	s_nop 0
	v_pk_mul_f32 v[2:3], v[2:3], v[4:5]
	v_exp_f32_e32 v4, v1
	s_nop 0
	v_pk_mul_f32 v[2:3], v[4:5], v[2:3] op_sel_hi:[0,1]
	v_pk_fma_f32 v[4:5], v[0:1], v[2:3], v[0:1] op_sel_hi:[0,1,1] neg_lo:[1,0,0] neg_hi:[1,0,0]
	v_mul_f32_e32 v0, v0, v2
	v_cndmask_b32_e32 v0, v4, v0, vcc
	s_waitcnt lgkmcnt(0)
	v_mul_f32_e32 v0, v0, v59
	v_mul_f32_e32 v60, 0x3caaaaab, v0
	ds_write_b32 v61, v60 offset:992
	s_cmp_lt_u32 s1, 31
	s_cbranch_scc1 .Lpeer_uloop
	ds_read_b32 v58, v61
	ds_read_b32 v59, v61 offset:512
	v_add_u32_e32 v61, 16, v61
	s_add_i32 s1, s1, 1
	s_waitcnt lgkmcnt(1)
	v_mad_i64_i32 v[0:1], s[6:7], v58, s14, v[80:81]
	global_load_dwordx4 v[218:221], v[0:1], off
	global_load_dwordx4 v[222:225], v[0:1], off offset:16
	global_load_dwordx4 v[226:229], v[0:1], off offset:32
	s_waitcnt vmcnt(4)
	v_cvt_scalef32_pk32_bf16_fp6 v[0:15], v[32:37], 1.0
	v_mov_b32_e32 v23, 0
	v_mov_b32_e32 v25, 0
	v_mov_b32_e32 v22, 0
	v_mov_b32_e32 v24, 0
	v_dot2c_f32_bf16_e32 v23, v0, v95
	v_dot2c_f32_bf16_e32 v25, v1, v159
	v_dot2c_f32_bf16_e32 v22, v2, v160
	v_dot2c_f32_bf16_e32 v24, v3, v161
	v_dot2c_f32_bf16_e32 v23, v4, v180
	v_dot2c_f32_bf16_e32 v25, v5, v181
	v_dot2c_f32_bf16_e32 v22, v6, v182
	v_dot2c_f32_bf16_e32 v24, v7, v183
	v_dot2c_f32_bf16_e32 v23, v8, v184
	v_dot2c_f32_bf16_e32 v25, v9, v185
	v_dot2c_f32_bf16_e32 v22, v10, v186
	v_dot2c_f32_bf16_e32 v24, v11, v187
	v_dot2c_f32_bf16_e32 v23, v12, v188
	v_dot2c_f32_bf16_e32 v25, v13, v189
	v_dot2c_f32_bf16_e32 v22, v14, v190
	v_dot2c_f32_bf16_e32 v24, v15, v191
	s_waitcnt vmcnt(3)
	v_cvt_scalef32_pk32_bf16_fp6 v[0:15], v[38:43], 1.0
	v_dot2c_f32_bf16_e32 v23, v0, v192
	v_dot2c_f32_bf16_e32 v25, v1, v193
	v_dot2c_f32_bf16_e32 v22, v2, v194
	v_dot2c_f32_bf16_e32 v24, v3, v195
	v_dot2c_f32_bf16_e32 v23, v4, v196
	v_dot2c_f32_bf16_e32 v25, v5, v197
	v_dot2c_f32_bf16_e32 v22, v6, v198
	v_dot2c_f32_bf16_e32 v24, v7, v199
	v_dot2c_f32_bf16_e32 v23, v8, v200
	v_dot2c_f32_bf16_e32 v25, v9, v201
	v_dot2c_f32_bf16_e32 v22, v10, v202
	v_dot2c_f32_bf16_e32 v24, v11, v203
	v_dot2c_f32_bf16_e32 v23, v12, v204
	v_dot2c_f32_bf16_e32 v25, v13, v205
	v_dot2c_f32_bf16_e32 v22, v14, v206
	v_dot2c_f32_bf16_e32 v24, v15, v207
	s_nop 2
	v_pk_add_f32 v[0:1], v[24:25], v[22:23]
	s_nop 0
	v_add_f32_e32 v0, v0, v1
	s_nop 1
	v_add_f32_dpp v0, v0, v0 quad_perm:[1,0,3,2] row_mask:0xf bank_mask:0xf bound_ctrl:1
	s_nop 1
	v_add_f32_dpp v0, v0, v0 quad_perm:[2,3,0,1] row_mask:0xf bank_mask:0xf bound_ctrl:1
	s_nop 1
	v_add_f32_dpp v0, v0, v0 row_half_mirror row_mask:0xf bank_mask:0xf bound_ctrl:1
	s_nop 1
	v_add_f32_dpp v0, v0, v0 row_mirror row_mask:0xf bank_mask:0xf bound_ctrl:1
	v_mul_f32_e32 v0, 0x3caaaaab, v0
	v_and_b32_e32 v2, 0x7fffffff, v0
	v_pk_fma_f32 v[2:3], v[2:3], s[16:17], 1.0 op_sel_hi:[0,0,0]
	v_rcp_f32_e32 v2, v2
	v_rcp_f32_e32 v3, v3
	v_mul_f32_e32 v1, v0, v0
	v_mul_f32_e32 v1, 0xbf38aa3b, v1
	v_cmp_gt_f32_e32 vcc, 0, v0
	v_pk_fma_f32 v[4:5], v[2:3], s[24:25], v[130:131] op_sel_hi:[1,0,0]
	s_nop 0
	v_pk_fma_f32 v[4:5], v[2:3], v[4:5], s[28:29] op_sel_hi:[1,1,0]
	s_nop 0
	v_pk_fma_f32 v[4:5], v[2:3], v[4:5], s[30:31] op_sel_hi:[1,1,0]
	s_nop 0
	v_pk_fma_f32 v[4:5], v[2:3], v[4:5], s[36:37] op_sel_hi:[1,1,0]
	s_nop 0
	v_pk_mul_f32 v[2:3], v[2:3], v[4:5]
	v_exp_f32_e32 v4, v1
	s_nop 0
	v_pk_mul_f32 v[2:3], v[4:5], v[2:3] op_sel_hi:[0,1]
	v_pk_fma_f32 v[4:5], v[0:1], v[2:3], v[0:1] op_sel_hi:[0,1,1] neg_lo:[1,0,0] neg_hi:[1,0,0]
	v_mul_f32_e32 v0, v0, v2
	v_cndmask_b32_e32 v0, v4, v0, vcc
	s_waitcnt lgkmcnt(0)
; __device__ void ph_peer(const float* __restrict__ SC, const bf16_t* __restrict__ H  , const float* __restrict__ gffn, const unsigned char* __restrict__ U, const unsigned char* __restrict__ V, float* X, const float* __restrict__ fgain) {
;     ...
;         for (int it = 0; it < 32; ++it) {
;             const int src = (it * 4 + grp) & 63;
;             const int e = __shfl(it < 16 ? idx_lo : idx_hi, src);
;             const float gt = __shfl(it < 16 ? g_lo : g_hi, src);
;             const u32x4* up = (const u32x4*)(U + (size_t)e * 768 + 48 * sub);
;             const u32x4 u0 = up[0], u1 = up[1], u2 = up[2];
;             u32x2 vw[2][3];
; #pragma unroll
;             for (int r = 0; r < 2; ++r) { const int ea = __builtin_amdgcn_readlane(e, 32 * r), eb = __builtin_amdgcn_readlane(e, 32 * r + 16);
;                 const u32x2* vp = (const u32x2*)(V + (size_t)(half ? eb : ea) * 768 + 24 * c32); vw[r][0] = vp[0]; vw[r][1] = vp[1]; vw[r][2] = vp[2]; }
;             float d0 = 0.f, d1 = 0.f, d2 = 0.f, d3 = 0.f;
;             {   const v6u_t p0 = (v6u_t){u0.x, u0.y, u0.z, u0.w, u1.x, u1.y};
;                 const v32bf_t r0 = __builtin_amdgcn_cvt_scalef32_pk32_bf16_fp6(p0, 1.0f);
; #pragma unroll
;                 for (int k = 0; k < 16; k += 4) { d0 = dot2pb(r0[2 * k], r0[2 * k + 1], hf2[k], d0); d1 = dot2pb(r0[2 * k + 2], r0[2 * k + 3], hf2[k + 1], d1);
;                     d2 = dot2pb(r0[2 * k + 4], r0[2 * k + 5], hf2[k + 2], d2); d3 = dot2pb(r0[2 * k + 6], r0[2 * k + 7], hf2[k + 3], d3); } }
;             {   const v6u_t p1 = (v6u_t){u1.z, u1.w, u2.x, u2.y, u2.z, u2.w};
;                 const v32bf_t r1 = __builtin_amdgcn_cvt_scalef32_pk32_bf16_fp6(p1, 1.0f);
; #pragma unroll
;                 for (int k = 0; k < 16; k += 4) { d0 = dot2pb(r1[2 * k], r1[2 * k + 1], hf2[16 + k], d0); d1 = dot2pb(r1[2 * k + 2], r1[2 * k + 3], hf2[16 + k + 1], d1);
;                     d2 = dot2pb(r1[2 * k + 4], r1[2 * k + 5], hf2[16 + k + 2], d2); d3 = dot2pb(r1[2 * k + 6], r1[2 * k + 7], hf2[16 + k + 3], d3); } }
;             const float d = row16_sum((d0 + d1) + (d2 + d3)) * FP6_INV;
;             const float a = gt * gelu1(d) * FP6_INV;
; #pragma unroll
;             for (int r = 0; r < 2; ++r) { const float aa = __int_as_float(__builtin_amdgcn_readlane(__float_as_int(a), 32 * r)), ab = __int_as_float(__builtin_amdgcn_readlane(__float_as_int(a), 32 * r + 16));
	v_mul_f32_e32 v0, v0, v57
	v_mul_f32_e32 v60, 0x3caaaaab, v0
	ds_write_b32 v61, v60 offset:992
	s_waitcnt vmcnt(1)
	v_cvt_scalef32_pk32_bf16_fp6 v[0:15], v[218:223], 1.0
	v_mov_b32_e32 v23, 0
	v_mov_b32_e32 v25, 0
	v_mov_b32_e32 v22, 0
	v_mov_b32_e32 v24, 0
	v_dot2c_f32_bf16_e32 v23, v0, v95
	v_dot2c_f32_bf16_e32 v25, v1, v159
	v_dot2c_f32_bf16_e32 v22, v2, v160
	v_dot2c_f32_bf16_e32 v24, v3, v161
	v_dot2c_f32_bf16_e32 v23, v4, v180
	v_dot2c_f32_bf16_e32 v25, v5, v181
	v_dot2c_f32_bf16_e32 v22, v6, v182
	v_dot2c_f32_bf16_e32 v24, v7, v183
	v_dot2c_f32_bf16_e32 v23, v8, v184
	v_dot2c_f32_bf16_e32 v25, v9, v185
	v_dot2c_f32_bf16_e32 v22, v10, v186
	v_dot2c_f32_bf16_e32 v24, v11, v187
	v_dot2c_f32_bf16_e32 v23, v12, v188
	v_dot2c_f32_bf16_e32 v25, v13, v189
	v_dot2c_f32_bf16_e32 v22, v14, v190
	v_dot2c_f32_bf16_e32 v24, v15, v191
	s_waitcnt vmcnt(0)
	v_cvt_scalef32_pk32_bf16_fp6 v[0:15], v[224:229], 1.0
	v_dot2c_f32_bf16_e32 v23, v0, v192
	v_dot2c_f32_bf16_e32 v25, v1, v193
	v_dot2c_f32_bf16_e32 v22, v2, v194
	v_dot2c_f32_bf16_e32 v24, v3, v195
	v_dot2c_f32_bf16_e32 v23, v4, v196
	v_dot2c_f32_bf16_e32 v25, v5, v197
	v_dot2c_f32_bf16_e32 v22, v6, v198
	v_dot2c_f32_bf16_e32 v24, v7, v199
	v_dot2c_f32_bf16_e32 v23, v8, v200
	v_dot2c_f32_bf16_e32 v25, v9, v201
	v_dot2c_f32_bf16_e32 v22, v10, v202
	v_dot2c_f32_bf16_e32 v24, v11, v203
	v_dot2c_f32_bf16_e32 v23, v12, v204
	v_dot2c_f32_bf16_e32 v25, v13, v205
	v_dot2c_f32_bf16_e32 v22, v14, v206
	v_dot2c_f32_bf16_e32 v24, v15, v207
	s_nop 2
	v_pk_add_f32 v[0:1], v[24:25], v[22:23]
	s_nop 0
	v_add_f32_e32 v0, v0, v1
	s_nop 1
	v_add_f32_dpp v0, v0, v0 quad_perm:[1,0,3,2] row_mask:0xf bank_mask:0xf bound_ctrl:1
	s_nop 1
	v_add_f32_dpp v0, v0, v0 quad_perm:[2,3,0,1] row_mask:0xf bank_mask:0xf bound_ctrl:1
	s_nop 1
	v_add_f32_dpp v0, v0, v0 row_half_mirror row_mask:0xf bank_mask:0xf bound_ctrl:1
	s_nop 1
	v_add_f32_dpp v0, v0, v0 row_mirror row_mask:0xf bank_mask:0xf bound_ctrl:1
	v_mul_f32_e32 v0, 0x3caaaaab, v0
	v_and_b32_e32 v2, 0x7fffffff, v0
	v_pk_fma_f32 v[2:3], v[2:3], s[16:17], 1.0 op_sel_hi:[0,0,0]
	v_rcp_f32_e32 v2, v2
	v_rcp_f32_e32 v3, v3
	v_mul_f32_e32 v1, v0, v0
	v_mul_f32_e32 v1, 0xbf38aa3b, v1
	v_cmp_gt_f32_e32 vcc, 0, v0
	v_pk_fma_f32 v[4:5], v[2:3], s[24:25], v[130:131] op_sel_hi:[1,0,0]
	s_nop 0
	v_pk_fma_f32 v[4:5], v[2:3], v[4:5], s[28:29] op_sel_hi:[1,1,0]
	s_nop 0
	v_pk_fma_f32 v[4:5], v[2:3], v[4:5], s[30:31] op_sel_hi:[1,1,0]
	s_nop 0
	v_pk_fma_f32 v[4:5], v[2:3], v[4:5], s[36:37] op_sel_hi:[1,1,0]
	s_nop 0
	v_pk_mul_f32 v[2:3], v[2:3], v[4:5]
	v_exp_f32_e32 v4, v1
	s_nop 0
	v_pk_mul_f32 v[2:3], v[4:5], v[2:3] op_sel_hi:[0,1]
	v_pk_fma_f32 v[4:5], v[0:1], v[2:3], v[0:1] op_sel_hi:[0,1,1] neg_lo:[1,0,0] neg_hi:[1,0,0]
	v_mul_f32_e32 v0, v0, v2
	v_cndmask_b32_e32 v0, v4, v0, vcc
	s_waitcnt lgkmcnt(0)
	v_mul_f32_e32 v0, v0, v59
	v_mul_f32_e32 v60, 0x3caaaaab, v0
	ds_write_b32 v61, v60 offset:1008
	v_lshrrev_b32_e32 v61, 6, v131
	v_lshrrev_b32_e32 v0, 5, v74
	v_mul_u32_u24_e32 v61, 0x2400, v61
	v_lshl_add_u32 v61, v0, 2, v61
	s_mov_b32 s1, 0
	ds_read_b32 v32, v61
	ds_read_b32 v33, v61 offset:8
	ds_read_b32 v56, v61 offset:1024
	ds_read_b32 v58, v61 offset:1032
	v_add_u32_e32 v61, 16, v61
	s_add_i32 s1, s1, 1
	s_waitcnt lgkmcnt(2)
	v_mad_i64_i32 v[0:1], s[6:7], v32, s14, v[82:83]
	v_mad_i64_i32 v[2:3], s[6:7], v33, s14, v[82:83]
	global_load_dwordx4 v[44:47], v[0:1], off
	global_load_dwordx2 v[48:49], v[0:1], off offset:16
	global_load_dwordx4 v[50:53], v[2:3], off
	global_load_dwordx2 v[54:55], v[2:3], off offset:16
.Lpeer_vloop:
	ds_read_b32 v218, v61
	ds_read_b32 v219, v61 offset:8
	ds_read_b32 v220, v61 offset:1024
	ds_read_b32 v222, v61 offset:1032
	v_add_u32_e32 v61, 16, v61
	s_add_i32 s1, s1, 1
	s_waitcnt lgkmcnt(2)
	v_mad_i64_i32 v[0:1], s[6:7], v218, s14, v[82:83]
	v_mad_i64_i32 v[2:3], s[6:7], v219, s14, v[82:83]
	global_load_dwordx4 v[230:233], v[0:1], off
	global_load_dwordx2 v[234:235], v[0:1], off offset:16
	global_load_dwordx4 v[236:239], v[2:3], off
	global_load_dwordx2 v[240:241], v[2:3], off offset:16
	s_waitcnt vmcnt(6)
	v_cvt_scalef32_pk32_f32_fp6 v[0:31], v[44:49], 1.0
	s_nop 1
	v_pk_fma_f32 v[126:127], v[0:1], v[56:57], v[126:127] op_sel_hi:[1,0,1]
	v_pk_fma_f32 v[122:123], v[2:3], v[56:57], v[122:123] op_sel_hi:[1,0,1]
	v_pk_fma_f32 v[114:115], v[4:5], v[56:57], v[114:115] op_sel_hi:[1,0,1]
	v_pk_fma_f32 v[116:117], v[6:7], v[56:57], v[116:117] op_sel_hi:[1,0,1]
	v_pk_fma_f32 v[106:107], v[8:9], v[56:57], v[106:107] op_sel_hi:[1,0,1]
	v_pk_fma_f32 v[108:109], v[10:11], v[56:57], v[108:109] op_sel_hi:[1,0,1]
	v_pk_fma_f32 v[98:99], v[12:13], v[56:57], v[98:99] op_sel_hi:[1,0,1]
	v_pk_fma_f32 v[100:101], v[14:15], v[56:57], v[100:101] op_sel_hi:[1,0,1]
	v_pk_fma_f32 v[144:145], v[16:17], v[56:57], v[144:145] op_sel_hi:[1,0,1]
	v_pk_fma_f32 v[124:125], v[18:19], v[56:57], v[124:125] op_sel_hi:[1,0,1]
	v_pk_fma_f32 v[118:119], v[20:21], v[56:57], v[118:119] op_sel_hi:[1,0,1]
	v_pk_fma_f32 v[120:121], v[22:23], v[56:57], v[120:121] op_sel_hi:[1,0,1]
	v_pk_fma_f32 v[110:111], v[24:25], v[56:57], v[110:111] op_sel_hi:[1,0,1]
	v_pk_fma_f32 v[112:113], v[26:27], v[56:57], v[112:113] op_sel_hi:[1,0,1]
	v_pk_fma_f32 v[102:103], v[28:29], v[56:57], v[102:103] op_sel_hi:[1,0,1]
	v_pk_fma_f32 v[104:105], v[30:31], v[56:57], v[104:105] op_sel_hi:[1,0,1]
	s_waitcnt vmcnt(4)
; __device__ void ph_peer(const float* __restrict__ SC, const bf16_t* __restrict__ H  , const float* __restrict__ gffn, const unsigned char* __restrict__ U, const unsigned char* __restrict__ V, float* X, const float* __restrict__ fgain) {
;     ...
; #pragma unroll
;             for (int r = 0; r < 2; ++r) { const float aa = __int_as_float(__builtin_amdgcn_readlane(__float_as_int(a), 32 * r)), ab = __int_as_float(__builtin_amdgcn_readlane(__float_as_int(a), 32 * r + 16));
;                 const float ak = half ? ab : aa;
;                 const v6u_t pv = (v6u_t){vw[r][0].x, vw[r][0].y, vw[r][1].x, vw[r][1].y, vw[r][2].x, vw[r][2].y};
;                 const v32f_t rv = __builtin_amdgcn_cvt_scalef32_pk32_f32_fp6(pv, 1.0f);
; #pragma unroll
;                 for (int i = 0; i < 32; ++i) acc[i] += ak * rv[i]; }
	v_cvt_scalef32_pk32_f32_fp6 v[0:31], v[50:55], 1.0
	s_nop 1
	v_pk_fma_f32 v[126:127], v[0:1], v[58:59], v[126:127] op_sel_hi:[1,0,1]
	v_pk_fma_f32 v[122:123], v[2:3], v[58:59], v[122:123] op_sel_hi:[1,0,1]
	v_pk_fma_f32 v[114:115], v[4:5], v[58:59], v[114:115] op_sel_hi:[1,0,1]
	v_pk_fma_f32 v[116:117], v[6:7], v[58:59], v[116:117] op_sel_hi:[1,0,1]
	v_pk_fma_f32 v[106:107], v[8:9], v[58:59], v[106:107] op_sel_hi:[1,0,1]
	v_pk_fma_f32 v[108:109], v[10:11], v[58:59], v[108:109] op_sel_hi:[1,0,1]
	v_pk_fma_f32 v[98:99], v[12:13], v[58:59], v[98:99] op_sel_hi:[1,0,1]
	v_pk_fma_f32 v[100:101], v[14:15], v[58:59], v[100:101] op_sel_hi:[1,0,1]
	v_pk_fma_f32 v[144:145], v[16:17], v[58:59], v[144:145] op_sel_hi:[1,0,1]
	v_pk_fma_f32 v[124:125], v[18:19], v[58:59], v[124:125] op_sel_hi:[1,0,1]
	v_pk_fma_f32 v[118:119], v[20:21], v[58:59], v[118:119] op_sel_hi:[1,0,1]
	v_pk_fma_f32 v[120:121], v[22:23], v[58:59], v[120:121] op_sel_hi:[1,0,1]
	v_pk_fma_f32 v[110:111], v[24:25], v[58:59], v[110:111] op_sel_hi:[1,0,1]
	v_pk_fma_f32 v[112:113], v[26:27], v[58:59], v[112:113] op_sel_hi:[1,0,1]
	v_pk_fma_f32 v[102:103], v[28:29], v[58:59], v[102:103] op_sel_hi:[1,0,1]
	v_pk_fma_f32 v[104:105], v[30:31], v[58:59], v[104:105] op_sel_hi:[1,0,1]
	ds_read_b32 v32, v61
	ds_read_b32 v33, v61 offset:8
	ds_read_b32 v56, v61 offset:1024
	ds_read_b32 v58, v61 offset:1032
	v_add_u32_e32 v61, 16, v61
	s_add_i32 s1, s1, 1
	s_waitcnt lgkmcnt(2)
	v_mad_i64_i32 v[0:1], s[6:7], v32, s14, v[82:83]
	v_mad_i64_i32 v[2:3], s[6:7], v33, s14, v[82:83]
	global_load_dwordx4 v[44:47], v[0:1], off
	global_load_dwordx2 v[48:49], v[0:1], off offset:16
	global_load_dwordx4 v[50:53], v[2:3], off
	global_load_dwordx2 v[54:55], v[2:3], off offset:16
	s_waitcnt vmcnt(6)
	v_cvt_scalef32_pk32_f32_fp6 v[0:31], v[230:235], 1.0
	s_nop 1
	v_pk_fma_f32 v[126:127], v[0:1], v[220:221], v[126:127] op_sel_hi:[1,0,1]
	v_pk_fma_f32 v[122:123], v[2:3], v[220:221], v[122:123] op_sel_hi:[1,0,1]
	v_pk_fma_f32 v[114:115], v[4:5], v[220:221], v[114:115] op_sel_hi:[1,0,1]
	v_pk_fma_f32 v[116:117], v[6:7], v[220:221], v[116:117] op_sel_hi:[1,0,1]
	v_pk_fma_f32 v[106:107], v[8:9], v[220:221], v[106:107] op_sel_hi:[1,0,1]
	v_pk_fma_f32 v[108:109], v[10:11], v[220:221], v[108:109] op_sel_hi:[1,0,1]
	v_pk_fma_f32 v[98:99], v[12:13], v[220:221], v[98:99] op_sel_hi:[1,0,1]
	v_pk_fma_f32 v[100:101], v[14:15], v[220:221], v[100:101] op_sel_hi:[1,0,1]
	v_pk_fma_f32 v[144:145], v[16:17], v[220:221], v[144:145] op_sel_hi:[1,0,1]
	v_pk_fma_f32 v[124:125], v[18:19], v[220:221], v[124:125] op_sel_hi:[1,0,1]
	v_pk_fma_f32 v[118:119], v[20:21], v[220:221], v[118:119] op_sel_hi:[1,0,1]
	v_pk_fma_f32 v[120:121], v[22:23], v[220:221], v[120:121] op_sel_hi:[1,0,1]
	v_pk_fma_f32 v[110:111], v[24:25], v[220:221], v[110:111] op_sel_hi:[1,0,1]
	v_pk_fma_f32 v[112:113], v[26:27], v[220:221], v[112:113] op_sel_hi:[1,0,1]
	v_pk_fma_f32 v[102:103], v[28:29], v[220:221], v[102:103] op_sel_hi:[1,0,1]
	v_pk_fma_f32 v[104:105], v[30:31], v[220:221], v[104:105] op_sel_hi:[1,0,1]
	s_waitcnt vmcnt(4)
	v_cvt_scalef32_pk32_f32_fp6 v[0:31], v[236:241], 1.0
	s_nop 1
	v_pk_fma_f32 v[126:127], v[0:1], v[222:223], v[126:127] op_sel_hi:[1,0,1]
	v_pk_fma_f32 v[122:123], v[2:3], v[222:223], v[122:123] op_sel_hi:[1,0,1]
	v_pk_fma_f32 v[114:115], v[4:5], v[222:223], v[114:115] op_sel_hi:[1,0,1]
	v_pk_fma_f32 v[116:117], v[6:7], v[222:223], v[116:117] op_sel_hi:[1,0,1]
	v_pk_fma_f32 v[106:107], v[8:9], v[222:223], v[106:107] op_sel_hi:[1,0,1]
	v_pk_fma_f32 v[108:109], v[10:11], v[222:223], v[108:109] op_sel_hi:[1,0,1]
	v_pk_fma_f32 v[98:99], v[12:13], v[222:223], v[98:99] op_sel_hi:[1,0,1]
	v_pk_fma_f32 v[100:101], v[14:15], v[222:223], v[100:101] op_sel_hi:[1,0,1]
	v_pk_fma_f32 v[144:145], v[16:17], v[222:223], v[144:145] op_sel_hi:[1,0,1]
	v_pk_fma_f32 v[124:125], v[18:19], v[222:223], v[124:125] op_sel_hi:[1,0,1]
	v_pk_fma_f32 v[118:119], v[20:21], v[222:223], v[118:119] op_sel_hi:[1,0,1]
	v_pk_fma_f32 v[120:121], v[22:23], v[222:223], v[120:121] op_sel_hi:[1,0,1]
	v_pk_fma_f32 v[110:111], v[24:25], v[222:223], v[110:111] op_sel_hi:[1,0,1]
	v_pk_fma_f32 v[112:113], v[26:27], v[222:223], v[112:113] op_sel_hi:[1,0,1]
	v_pk_fma_f32 v[102:103], v[28:29], v[222:223], v[102:103] op_sel_hi:[1,0,1]
	v_pk_fma_f32 v[104:105], v[30:31], v[222:223], v[104:105] op_sel_hi:[1,0,1]
	s_cmp_lt_u32 s1, 31
	s_cbranch_scc1 .Lpeer_vloop
; __device__ void ph_peer(const float* __restrict__ SC, const bf16_t* __restrict__ H  , const float* __restrict__ gffn, const unsigned char* __restrict__ U, const unsigned char* __restrict__ V, float* X, const float* __restrict__ fgain) {
;     ...
; #pragma unroll
;             for (int r = 0; r < 2; ++r) { const float aa = __int_as_float(__builtin_amdgcn_readlane(__float_as_int(a), 32 * r)), ab = __int_as_float(__builtin_amdgcn_readlane(__float_as_int(a), 32 * r + 16));
;                 const float ak = half ? ab : aa;
;                 const v6u_t pv = (v6u_t){vw[r][0].x, vw[r][0].y, vw[r][1].x, vw[r][1].y, vw[r][2].x, vw[r][2].y};
;                 const v32f_t rv = __builtin_amdgcn_cvt_scalef32_pk32_f32_fp6(pv, 1.0f);
; #pragma unroll
;                 for (int i = 0; i < 32; ++i) acc[i] += ak * rv[i]; }
;         }
;         __builtin_amdgcn_s_setprio(0);
;         float o16[16];
; #pragma unroll
;         for (int i = 0; i < 16; ++i) { const float lo = acc[i] + __shfl_xor(acc[i], 32), hi = acc[16 + i] + __shfl_xor(acc[16 + i], 32); o16[i] = half ? hi : lo; }
	ds_read_b32 v218, v61
	ds_read_b32 v219, v61 offset:8
	ds_read_b32 v220, v61 offset:1024
	ds_read_b32 v222, v61 offset:1032
	v_add_u32_e32 v61, 16, v61
	s_add_i32 s1, s1, 1
	s_waitcnt lgkmcnt(2)
	v_mad_i64_i32 v[0:1], s[6:7], v218, s14, v[82:83]
	v_mad_i64_i32 v[2:3], s[6:7], v219, s14, v[82:83]
	global_load_dwordx4 v[230:233], v[0:1], off
	global_load_dwordx2 v[234:235], v[0:1], off offset:16
	global_load_dwordx4 v[236:239], v[2:3], off
	global_load_dwordx2 v[240:241], v[2:3], off offset:16
	s_waitcnt vmcnt(6)
	v_cvt_scalef32_pk32_f32_fp6 v[0:31], v[44:49], 1.0
	s_nop 1
	v_pk_fma_f32 v[126:127], v[0:1], v[56:57], v[126:127] op_sel_hi:[1,0,1]
	v_pk_fma_f32 v[122:123], v[2:3], v[56:57], v[122:123] op_sel_hi:[1,0,1]
	v_pk_fma_f32 v[114:115], v[4:5], v[56:57], v[114:115] op_sel_hi:[1,0,1]
	v_pk_fma_f32 v[116:117], v[6:7], v[56:57], v[116:117] op_sel_hi:[1,0,1]
	v_pk_fma_f32 v[106:107], v[8:9], v[56:57], v[106:107] op_sel_hi:[1,0,1]
	v_pk_fma_f32 v[108:109], v[10:11], v[56:57], v[108:109] op_sel_hi:[1,0,1]
	v_pk_fma_f32 v[98:99], v[12:13], v[56:57], v[98:99] op_sel_hi:[1,0,1]
	v_pk_fma_f32 v[100:101], v[14:15], v[56:57], v[100:101] op_sel_hi:[1,0,1]
	v_pk_fma_f32 v[144:145], v[16:17], v[56:57], v[144:145] op_sel_hi:[1,0,1]
	v_pk_fma_f32 v[124:125], v[18:19], v[56:57], v[124:125] op_sel_hi:[1,0,1]
	v_pk_fma_f32 v[118:119], v[20:21], v[56:57], v[118:119] op_sel_hi:[1,0,1]
	v_pk_fma_f32 v[120:121], v[22:23], v[56:57], v[120:121] op_sel_hi:[1,0,1]
	v_pk_fma_f32 v[110:111], v[24:25], v[56:57], v[110:111] op_sel_hi:[1,0,1]
	v_pk_fma_f32 v[112:113], v[26:27], v[56:57], v[112:113] op_sel_hi:[1,0,1]
	v_pk_fma_f32 v[102:103], v[28:29], v[56:57], v[102:103] op_sel_hi:[1,0,1]
	v_pk_fma_f32 v[104:105], v[30:31], v[56:57], v[104:105] op_sel_hi:[1,0,1]
	s_waitcnt vmcnt(4)
	v_cvt_scalef32_pk32_f32_fp6 v[0:31], v[50:55], 1.0
	s_nop 1
	v_pk_fma_f32 v[126:127], v[0:1], v[58:59], v[126:127] op_sel_hi:[1,0,1]
	v_pk_fma_f32 v[122:123], v[2:3], v[58:59], v[122:123] op_sel_hi:[1,0,1]
	v_pk_fma_f32 v[114:115], v[4:5], v[58:59], v[114:115] op_sel_hi:[1,0,1]
	v_pk_fma_f32 v[116:117], v[6:7], v[58:59], v[116:117] op_sel_hi:[1,0,1]
	v_pk_fma_f32 v[106:107], v[8:9], v[58:59], v[106:107] op_sel_hi:[1,0,1]
	v_pk_fma_f32 v[108:109], v[10:11], v[58:59], v[108:109] op_sel_hi:[1,0,1]
	v_pk_fma_f32 v[98:99], v[12:13], v[58:59], v[98:99] op_sel_hi:[1,0,1]
	v_pk_fma_f32 v[100:101], v[14:15], v[58:59], v[100:101] op_sel_hi:[1,0,1]
	v_pk_fma_f32 v[144:145], v[16:17], v[58:59], v[144:145] op_sel_hi:[1,0,1]
	v_pk_fma_f32 v[124:125], v[18:19], v[58:59], v[124:125] op_sel_hi:[1,0,1]
	v_pk_fma_f32 v[118:119], v[20:21], v[58:59], v[118:119] op_sel_hi:[1,0,1]
	v_pk_fma_f32 v[120:121], v[22:23], v[58:59], v[120:121] op_sel_hi:[1,0,1]
	v_pk_fma_f32 v[110:111], v[24:25], v[58:59], v[110:111] op_sel_hi:[1,0,1]
	v_pk_fma_f32 v[112:113], v[26:27], v[58:59], v[112:113] op_sel_hi:[1,0,1]
	v_pk_fma_f32 v[102:103], v[28:29], v[58:59], v[102:103] op_sel_hi:[1,0,1]
	v_pk_fma_f32 v[104:105], v[30:31], v[58:59], v[104:105] op_sel_hi:[1,0,1]
	s_waitcnt vmcnt(2) lgkmcnt(0)
	v_cvt_scalef32_pk32_f32_fp6 v[0:31], v[230:235], 1.0
	s_nop 1
	v_pk_fma_f32 v[126:127], v[0:1], v[220:221], v[126:127] op_sel_hi:[1,0,1]
	v_pk_fma_f32 v[122:123], v[2:3], v[220:221], v[122:123] op_sel_hi:[1,0,1]
	v_pk_fma_f32 v[114:115], v[4:5], v[220:221], v[114:115] op_sel_hi:[1,0,1]
	v_pk_fma_f32 v[116:117], v[6:7], v[220:221], v[116:117] op_sel_hi:[1,0,1]
	v_pk_fma_f32 v[106:107], v[8:9], v[220:221], v[106:107] op_sel_hi:[1,0,1]
	v_pk_fma_f32 v[108:109], v[10:11], v[220:221], v[108:109] op_sel_hi:[1,0,1]
	v_pk_fma_f32 v[98:99], v[12:13], v[220:221], v[98:99] op_sel_hi:[1,0,1]
	v_pk_fma_f32 v[100:101], v[14:15], v[220:221], v[100:101] op_sel_hi:[1,0,1]
	v_pk_fma_f32 v[144:145], v[16:17], v[220:221], v[144:145] op_sel_hi:[1,0,1]
	v_pk_fma_f32 v[124:125], v[18:19], v[220:221], v[124:125] op_sel_hi:[1,0,1]
	v_pk_fma_f32 v[118:119], v[20:21], v[220:221], v[118:119] op_sel_hi:[1,0,1]
	v_pk_fma_f32 v[120:121], v[22:23], v[220:221], v[120:121] op_sel_hi:[1,0,1]
	v_pk_fma_f32 v[110:111], v[24:25], v[220:221], v[110:111] op_sel_hi:[1,0,1]
	v_pk_fma_f32 v[112:113], v[26:27], v[220:221], v[112:113] op_sel_hi:[1,0,1]
	v_pk_fma_f32 v[102:103], v[28:29], v[220:221], v[102:103] op_sel_hi:[1,0,1]
	v_pk_fma_f32 v[104:105], v[30:31], v[220:221], v[104:105] op_sel_hi:[1,0,1]
	s_waitcnt vmcnt(0)
	v_cvt_scalef32_pk32_f32_fp6 v[0:31], v[236:241], 1.0
	s_nop 1
	v_pk_fma_f32 v[126:127], v[0:1], v[222:223], v[126:127] op_sel_hi:[1,0,1]
	v_pk_fma_f32 v[122:123], v[2:3], v[222:223], v[122:123] op_sel_hi:[1,0,1]
	v_pk_fma_f32 v[114:115], v[4:5], v[222:223], v[114:115] op_sel_hi:[1,0,1]
	v_pk_fma_f32 v[116:117], v[6:7], v[222:223], v[116:117] op_sel_hi:[1,0,1]
	v_pk_fma_f32 v[106:107], v[8:9], v[222:223], v[106:107] op_sel_hi:[1,0,1]
	v_pk_fma_f32 v[108:109], v[10:11], v[222:223], v[108:109] op_sel_hi:[1,0,1]
	v_pk_fma_f32 v[98:99], v[12:13], v[222:223], v[98:99] op_sel_hi:[1,0,1]
	v_pk_fma_f32 v[100:101], v[14:15], v[222:223], v[100:101] op_sel_hi:[1,0,1]
	v_pk_fma_f32 v[144:145], v[16:17], v[222:223], v[144:145] op_sel_hi:[1,0,1]
	v_pk_fma_f32 v[124:125], v[18:19], v[222:223], v[124:125] op_sel_hi:[1,0,1]
	v_pk_fma_f32 v[118:119], v[20:21], v[222:223], v[118:119] op_sel_hi:[1,0,1]
	v_pk_fma_f32 v[120:121], v[22:23], v[222:223], v[120:121] op_sel_hi:[1,0,1]
	v_pk_fma_f32 v[110:111], v[24:25], v[222:223], v[110:111] op_sel_hi:[1,0,1]
	v_pk_fma_f32 v[112:113], v[26:27], v[222:223], v[112:113] op_sel_hi:[1,0,1]
	v_pk_fma_f32 v[102:103], v[28:29], v[222:223], v[102:103] op_sel_hi:[1,0,1]
	v_pk_fma_f32 v[104:105], v[30:31], v[222:223], v[104:105] op_sel_hi:[1,0,1]
	s_setprio 0
	ds_bpermute_b32 v0, v154, v126
	ds_bpermute_b32 v2, v154, v144
	ds_bpermute_b32 v1, v154, v127
	ds_bpermute_b32 v3, v154, v145
	v_lshl_add_u64 v[28:29], v[96:97], 2, v[84:85]
	ds_bpermute_b32 v16, v154, v122
	ds_bpermute_b32 v18, v154, v124
	s_waitcnt lgkmcnt(3)
; __device__ void ph_peer(const float* __restrict__ SC, const bf16_t* __restrict__ H  , const float* __restrict__ gffn, const unsigned char* __restrict__ U, const unsigned char* __restrict__ V, float* X, const float* __restrict__ fgain) {
;     ...
;         for (int i = 0; i < 16; ++i) { const float lo = acc[i] + __shfl_xor(acc[i], 32), hi = acc[16 + i] + __shfl_xor(acc[16 + i], 32); o16[i] = half ? hi : lo; }
;         float4* xp = (float4*)(X + (size_t)tok * 1024 + 32 * c32 + 16 * half);
;         float4 xo[4]; float ss = 0.f;
; #pragma unroll
;         for (int j = 0; j < 4; ++j) { float4 a = xp[j]; a.x += o16[j * 4 + 0]; a.y += o16[j * 4 + 1]; a.z += o16[j * 4 + 2]; a.w += o16[j * 4 + 3]; xo[j] = a; ss += a.x * a.x + a.y * a.y + a.z * a.z + a.w * a.w; }
;         if (fgain) { ss = wave_sum(ss); const float rs = rsqrtf(ss * (1.0f / 1024.0f) + 1e-6f);
; #pragma unroll
;             for (int j = 0; j < 4; ++j) { const float4 g = *(const float4*)(fgain + 32 * c32 + 16 * half + j * 4); xo[j].x *= rs * g.x; xo[j].y *= rs * g.y; xo[j].z *= rs * g.z; xo[j].w *= rs * g.w; } }
; #pragma unroll
;         for (int j = 0; j < 4; ++j) xp[j] = xo[j];
	v_pk_add_f32 v[0:1], v[126:127], v[0:1]
	s_waitcnt lgkmcnt(2)
	v_pk_add_f32 v[2:3], v[144:145], v[2:3]
	ds_bpermute_b32 v17, v154, v123
	v_cndmask_b32_e64 v47, v3, v1, s[44:45]
	v_cndmask_b32_e64 v46, v2, v0, s[44:45]
	global_load_dwordx4 v[8:11], v[28:29], off offset:48
	global_load_dwordx4 v[12:15], v[28:29], off offset:32
	global_load_dwordx4 v[4:7], v[28:29], off offset:16
	global_load_dwordx4 v[0:3], v[28:29], off
	ds_bpermute_b32 v19, v154, v125
	ds_bpermute_b32 v20, v154, v114
	ds_bpermute_b32 v22, v154, v118
	ds_bpermute_b32 v21, v154, v115
	ds_bpermute_b32 v23, v154, v119
	ds_bpermute_b32 v24, v154, v116
	ds_bpermute_b32 v26, v154, v120
	ds_bpermute_b32 v25, v154, v117
	ds_bpermute_b32 v27, v154, v121
	ds_bpermute_b32 v30, v154, v106
	ds_bpermute_b32 v32, v154, v110
	ds_bpermute_b32 v31, v154, v107
	ds_bpermute_b32 v33, v154, v111
	s_waitcnt lgkmcnt(13)
	v_pk_add_f32 v[16:17], v[122:123], v[16:17]
	s_waitcnt lgkmcnt(12)
	v_pk_add_f32 v[18:19], v[124:125], v[18:19]
	ds_bpermute_b32 v34, v154, v108
	ds_bpermute_b32 v36, v154, v112
	ds_bpermute_b32 v35, v154, v109
	ds_bpermute_b32 v37, v154, v113
	v_cndmask_b32_e64 v17, v19, v17, s[44:45]
	v_cndmask_b32_e64 v16, v18, v16, s[44:45]
	s_waitcnt lgkmcnt(12)
	v_pk_add_f32 v[18:19], v[118:119], v[22:23]
	ds_bpermute_b32 v38, v154, v98
	ds_bpermute_b32 v40, v154, v102
	ds_bpermute_b32 v39, v154, v99
	ds_bpermute_b32 v41, v154, v103
	ds_bpermute_b32 v42, v154, v100
	ds_bpermute_b32 v44, v154, v104
	ds_bpermute_b32 v43, v154, v101
	ds_bpermute_b32 v45, v154, v105
	s_and_b64 vcc, exec, s[92:93]
	s_waitcnt vmcnt(0)
	v_pk_add_f32 v[2:3], v[16:17], v[2:3]
	v_pk_add_f32 v[16:17], v[114:115], v[20:21]
	s_waitcnt lgkmcnt(14)
	v_pk_add_f32 v[20:21], v[120:121], v[26:27]
	v_cndmask_b32_e64 v17, v19, v17, s[44:45]
	v_cndmask_b32_e64 v16, v18, v16, s[44:45]
	v_pk_add_f32 v[18:19], v[116:117], v[24:25]
	v_pk_add_f32 v[4:5], v[16:17], v[4:5]
	v_cndmask_b32_e64 v19, v21, v19, s[44:45]
	v_cndmask_b32_e64 v18, v20, v18, s[44:45]
	v_pk_add_f32 v[6:7], v[18:19], v[6:7]
	s_waitcnt lgkmcnt(13)
	v_pk_add_f32 v[16:17], v[106:107], v[30:31]
	s_waitcnt lgkmcnt(12)
	v_pk_add_f32 v[18:19], v[110:111], v[32:33]
	s_waitcnt lgkmcnt(8)
	v_pk_add_f32 v[20:21], v[112:113], v[36:37]
	v_cndmask_b32_e64 v17, v19, v17, s[44:45]
	v_cndmask_b32_e64 v16, v18, v16, s[44:45]
	v_pk_add_f32 v[18:19], v[108:109], v[34:35]
	v_pk_add_f32 v[12:13], v[16:17], v[12:13]
	v_cndmask_b32_e64 v19, v21, v19, s[44:45]
	v_cndmask_b32_e64 v18, v20, v18, s[44:45]
	v_pk_add_f32 v[14:15], v[18:19], v[14:15]
	s_waitcnt lgkmcnt(5)
	v_pk_add_f32 v[16:17], v[98:99], v[38:39]
	s_waitcnt lgkmcnt(4)
	v_pk_add_f32 v[18:19], v[102:103], v[40:41]
	s_waitcnt lgkmcnt(0)
	v_pk_add_f32 v[20:21], v[104:105], v[44:45]
	v_cndmask_b32_e64 v17, v19, v17, s[44:45]
	v_cndmask_b32_e64 v16, v18, v16, s[44:45]
	v_pk_add_f32 v[18:19], v[100:101], v[42:43]
	v_pk_add_f32 v[0:1], v[46:47], v[0:1]
	v_cndmask_b32_e64 v19, v21, v19, s[44:45]
	v_cndmask_b32_e64 v18, v20, v18, s[44:45]
	v_pk_add_f32 v[8:9], v[16:17], v[8:9]
	v_pk_add_f32 v[10:11], v[18:19], v[10:11]
	s_cbranch_vccz .LBB0_220
	v_mov_b32_e32 v18, v1
	v_mov_b32_e32 v19, v5
	v_mov_b32_e32 v16, v0
	v_mov_b32_e32 v17, v4
	v_pk_mul_f32 v[18:19], v[18:19], v[18:19]
	v_mov_b32_e32 v20, v13
	v_pk_fma_f32 v[16:17], v[16:17], v[16:17], v[18:19]
	v_mov_b32_e32 v18, v2
	v_mov_b32_e32 v19, v6
	v_pk_fma_f32 v[16:17], v[18:19], v[18:19], v[16:17]
	v_mov_b32_e32 v18, v3
	v_mov_b32_e32 v19, v7
	v_mov_b32_e32 v21, v9
	v_pk_fma_f32 v[16:17], v[18:19], v[18:19], v[16:17]
	v_mov_b32_e32 v18, v12
	v_mov_b32_e32 v19, v8
	v_pk_mul_f32 v[20:21], v[20:21], v[20:21]
	v_add_f32_e32 v16, v16, v17
	v_pk_fma_f32 v[18:19], v[18:19], v[18:19], v[20:21]
	v_mov_b32_e32 v20, v14
	v_mov_b32_e32 v21, v10
	v_pk_fma_f32 v[18:19], v[20:21], v[20:21], v[18:19]
	v_mov_b32_e32 v20, v15
	v_mov_b32_e32 v21, v11
	v_pk_fma_f32 v[18:19], v[20:21], v[20:21], v[18:19]
	s_nop 0
	v_add_f32_e32 v16, v16, v18
	v_add_f32_e32 v16, v16, v19
	s_nop 1
	v_add_f32_dpp v16, v16, v16 quad_perm:[1,0,3,2] row_mask:0xf bank_mask:0xf bound_ctrl:1
	s_nop 1
	v_add_f32_dpp v16, v16, v16 quad_perm:[2,3,0,1] row_mask:0xf bank_mask:0xf bound_ctrl:1
	s_nop 1
	v_add_f32_dpp v16, v16, v16 row_half_mirror row_mask:0xf bank_mask:0xf bound_ctrl:1
	s_nop 1
	v_add_f32_dpp v16, v16, v16 row_mirror row_mask:0xf bank_mask:0xf bound_ctrl:1
	s_nop 0
	v_readlane_b32 s2, v16, 16
	v_readlane_b32 s6, v16, 48
	v_readlane_b32 s0, v16, 0
	v_readlane_b32 s1, v16, 32
	v_mov_b32_e32 v16, s2
	v_mov_b32_e32 v17, s6
	v_pk_add_f32 v[16:17], s[0:1], v[16:17]
	s_mov_b32 s0, 0x800000
	v_add_f32_e32 v16, v16, v17
	v_fmamk_f32 v16, v16, 0x3a800000, v170
	v_cmp_gt_f32_e32 vcc, s0, v16
	v_mul_f32_e32 v17, 0x4b800000, v16
	s_nop 0
	v_cndmask_b32_e32 v16, v16, v17, vcc
	v_rsq_f32_e32 v16, v16
	s_nop 0
	v_mul_f32_e32 v17, 0x45800000, v16
	v_cndmask_b32_e32 v30, v16, v17, vcc
	global_load_dwordx4 v[16:19], v[86:87], off offset:48
	global_load_dwordx4 v[20:23], v[86:87], off offset:32
	global_load_dwordx4 v[24:27], v[86:87], off offset:16
	global_load_dwordx4 v[32:35], v[86:87], off
	s_waitcnt vmcnt(3)
	v_pk_mul_f32 v[16:17], v[30:31], v[16:17] op_sel_hi:[0,1]
	s_waitcnt vmcnt(2)
	v_pk_mul_f32 v[20:21], v[20:21], v[30:31] op_sel_hi:[1,0]
	s_waitcnt vmcnt(1)
	v_pk_mul_f32 v[24:25], v[24:25], v[30:31] op_sel_hi:[1,0]
	s_waitcnt vmcnt(0)
	v_pk_mul_f32 v[32:33], v[32:33], v[30:31] op_sel_hi:[1,0]
	v_pk_mul_f32 v[4:5], v[4:5], v[24:25]
	v_pk_mul_f32 v[0:1], v[0:1], v[32:33]
	v_pk_mul_f32 v[32:33], v[34:35], v[30:31] op_sel_hi:[1,0]
	v_pk_mul_f32 v[24:25], v[26:27], v[30:31] op_sel_hi:[1,0]
	v_pk_mul_f32 v[12:13], v[12:13], v[20:21]
	v_pk_mul_f32 v[20:21], v[30:31], v[22:23] op_sel_hi:[0,1]
	v_pk_mul_f32 v[8:9], v[8:9], v[16:17]
	v_pk_mul_f32 v[16:17], v[30:31], v[18:19] op_sel_hi:[0,1]
	v_pk_mul_f32 v[2:3], v[2:3], v[32:33]
	v_pk_mul_f32 v[6:7], v[6:7], v[24:25]
	v_pk_mul_f32 v[14:15], v[14:15], v[20:21]
	v_pk_mul_f32 v[10:11], v[10:11], v[16:17]
	s_branch .LBB0_220

; template <int L>
; __device__ __forceinline__ void hy_conv(const bf16_t* F, const bf16_t* Bbuf, const bf16_t* Vbuf, bf16_t* Obuf, float skipv) {
;     ...
;         for (; d < dlast; d += 32) {
;             const bf16x8 b0n = *(const bf16x8*)(bp0 + d + 32), b1n = *(const bf16x8*)(bp1 + d + 32); bf16x8 an[4];
; #pragma unroll
;             for (int rho = 0; rho < 4; ++rho) an[rho] = HY_AFR(rho, d + 32);
; #pragma unroll
;             for (int rho = 0; rho < 4; ++rho) {
;                 acc0[rho] = __builtin_amdgcn_mfma_f32_16x16x32_bf16(ac[rho], b0c, acc0[rho], 0, 0, 0);
;                 acc1[rho] = __builtin_amdgcn_mfma_f32_16x16x32_bf16(ac[rho], b1c, acc1[rho], 0, 0, 0); }
;             b0c = b0n; b1c = b1n;
; #pragma unroll
;             for (int rho = 0; rho < 4; ++rho) ac[rho] = an[rho];
;         }
.LBB0_469:
	s_waitcnt lgkmcnt(5)
	v_mov_b64_e32 v[242:243], v[86:87]
	s_waitcnt lgkmcnt(4)
	v_mov_b64_e32 v[246:247], v[50:51]
	v_mov_b64_e32 v[240:241], v[84:85]
	v_mov_b64_e32 v[244:245], v[48:49]
	v_add_u32_e32 v84, 0xfffffe00, v236
	s_waitcnt lgkmcnt(2)
	v_mfma_f32_16x16x32_bf16 v[68:71], v[76:79], v[240:243], v[68:71]
	v_add_u32_e32 v237, 0x8300, v235
	v_add_u32_e32 v239, 0xc480, v235
	v_add_u32_e32 v234, 32, v234
	v_mfma_f32_16x16x32_bf16 v[40:43], v[76:79], v[244:247], v[40:43]
	v_add_u32_e32 v76, 0x4180, v235
	v_cmp_ge_i32_e32 vcc, v234, v238
	s_or_b64 s[24:25], vcc, s[24:25]
	v_mfma_f32_16x16x32_bf16 v[72:75], v[80:83], v[240:243], v[72:75]
	v_mfma_f32_16x16x32_bf16 v[44:47], v[80:83], v[244:247], v[44:47]
	ds_read_b128 v[48:51], v236
	ds_read_b64 v[82:83], v235 offset:8
	ds_read_b64 v[80:81], v235
	ds_read_b128 v[84:87], v84
	v_add_u32_e32 v235, 64, v235
	s_waitcnt lgkmcnt(5)
	v_mfma_f32_16x16x32_bf16 v[60:63], v[64:67], v[240:243], v[60:63]
	v_add_u32_e32 v236, 64, v236
	v_mfma_f32_16x16x32_bf16 v[36:39], v[64:67], v[244:247], v[36:39]
	s_waitcnt lgkmcnt(4)
	v_mfma_f32_16x16x32_bf16 v[56:59], v[52:55], v[240:243], v[56:59]
	ds_read_b64 v[78:79], v76 offset:8
	ds_read_b64 v[76:77], v76
	ds_read_b64 v[66:67], v237 offset:8
	ds_read_b64 v[64:65], v237
	ds_read_b64 v[242:243], v239 offset:8
	ds_read_b64 v[240:241], v239
	v_mfma_f32_16x16x32_bf16 v[32:35], v[52:55], v[244:247], v[32:35]
	s_waitcnt lgkmcnt(0)
	v_mov_b32_e32 v52, v240
	v_mov_b32_e32 v53, v241
	v_mov_b32_e32 v54, v242
	v_mov_b32_e32 v55, v243
	s_andn2_b64 exec, exec, s[24:25]
	s_cbranch_execnz .LBB0_469
	s_or_b64 exec, exec, s[24:25]

; template <int L>
; __device__ __forceinline__ void hy_conv(const bf16_t* F, const bf16_t* Bbuf, const bf16_t* Vbuf, bf16_t* Obuf, float skipv) {
;     ...
;         for (; d < dlast; d += 32) {
;             const bf16x8 b0n = *(const bf16x8*)(bp0 + d + 32), b1n = *(const bf16x8*)(bp1 + d + 32); bf16x8 an[4];
; #pragma unroll
;             for (int rho = 0; rho < 4; ++rho) an[rho] = HY_AFR(rho, d + 32);
; #pragma unroll
;             for (int rho = 0; rho < 4; ++rho) {
;                 acc0[rho] = __builtin_amdgcn_mfma_f32_16x16x32_bf16(ac[rho], b0c, acc0[rho], 0, 0, 0);
;                 acc1[rho] = __builtin_amdgcn_mfma_f32_16x16x32_bf16(ac[rho], b1c, acc1[rho], 0, 0, 0); }
;             b0c = b0n; b1c = b1n;
; #pragma unroll
;             for (int rho = 0; rho < 4; ++rho) ac[rho] = an[rho];
;         }
.LBB0_543:
	s_waitcnt lgkmcnt(5)
	v_mov_b64_e32 v[214:215], v[86:87]
	s_waitcnt lgkmcnt(4)
	v_mov_b64_e32 v[218:219], v[50:51]
	v_mov_b64_e32 v[212:213], v[84:85]
	v_mov_b64_e32 v[216:217], v[48:49]
	v_add_u32_e32 v84, 0xfffffe00, v209
	s_waitcnt lgkmcnt(2)
	v_mfma_f32_16x16x32_bf16 v[68:71], v[76:79], v[212:215], v[68:71]
	v_add_u32_e32 v210, 0x8300, v208
	v_add_u32_e32 v220, 0xc480, v208
	v_add_u32_e32 v207, 32, v207
	v_mfma_f32_16x16x32_bf16 v[40:43], v[76:79], v[216:219], v[40:43]
	v_add_u32_e32 v76, 0x4180, v208
	v_cmp_ge_i32_e32 vcc, v207, v211
	s_or_b64 s[24:25], vcc, s[24:25]
	v_mfma_f32_16x16x32_bf16 v[72:75], v[80:83], v[212:215], v[72:75]
	v_mfma_f32_16x16x32_bf16 v[44:47], v[80:83], v[216:219], v[44:47]
	ds_read_b128 v[48:51], v209
	ds_read_b64 v[82:83], v208 offset:8
	ds_read_b64 v[80:81], v208
	ds_read_b128 v[84:87], v84
	v_add_u32_e32 v208, 64, v208
	s_waitcnt lgkmcnt(5)
	v_mfma_f32_16x16x32_bf16 v[60:63], v[64:67], v[212:215], v[60:63]
	v_add_u32_e32 v209, 64, v209
	v_mfma_f32_16x16x32_bf16 v[36:39], v[64:67], v[216:219], v[36:39]
	s_waitcnt lgkmcnt(4)
	v_mfma_f32_16x16x32_bf16 v[56:59], v[52:55], v[212:215], v[56:59]
	ds_read_b64 v[78:79], v76 offset:8
	ds_read_b64 v[76:77], v76
	ds_read_b64 v[66:67], v210 offset:8
	ds_read_b64 v[64:65], v210
	ds_read_b64 v[214:215], v220 offset:8
	ds_read_b64 v[212:213], v220
	v_mfma_f32_16x16x32_bf16 v[32:35], v[52:55], v[216:219], v[32:35]
	s_waitcnt lgkmcnt(0)
	v_mov_b32_e32 v52, v212
	v_mov_b32_e32 v53, v213
	v_mov_b32_e32 v54, v214
	v_mov_b32_e32 v55, v215
	s_andn2_b64 exec, exec, s[24:25]
	s_cbranch_execnz .LBB0_543
	s_or_b64 exec, exec, s[24:25]

; template <int L>
; __device__ __forceinline__ void hy_conv(const bf16_t* F, const bf16_t* Bbuf, const bf16_t* Vbuf, bf16_t* Obuf, float skipv) {
;     ...
;         for (; d < dlast; d += 32) {
;             const bf16x8 b0n = *(const bf16x8*)(bp0 + d + 32), b1n = *(const bf16x8*)(bp1 + d + 32); bf16x8 an[4];
; #pragma unroll
;             for (int rho = 0; rho < 4; ++rho) an[rho] = HY_AFR(rho, d + 32);
; #pragma unroll
;             for (int rho = 0; rho < 4; ++rho) {
;                 acc0[rho] = __builtin_amdgcn_mfma_f32_16x16x32_bf16(ac[rho], b0c, acc0[rho], 0, 0, 0);
;                 acc1[rho] = __builtin_amdgcn_mfma_f32_16x16x32_bf16(ac[rho], b1c, acc1[rho], 0, 0, 0); }
;             b0c = b0n; b1c = b1n;
; #pragma unroll
;             for (int rho = 0; rho < 4; ++rho) ac[rho] = an[rho];
;         }
.LBB0_647:
	s_waitcnt lgkmcnt(5)
	v_mov_b64_e32 v[200:201], v[58:59]
	s_waitcnt lgkmcnt(4)
	v_mov_b64_e32 v[204:205], v[50:51]
	v_mov_b64_e32 v[198:199], v[56:57]
	v_mov_b64_e32 v[202:203], v[48:49]
	v_add_u32_e32 v196, 0x4300, v194
	s_waitcnt lgkmcnt(2)
	v_mfma_f32_16x16x32_bf16 v[68:71], v[80:83], v[198:201], v[68:71]
	v_add_u32_e32 v206, 0x6480, v194
	v_add_u32_e32 v193, 32, v193
	v_cmp_ge_i32_e32 vcc, v193, v197
	v_mfma_f32_16x16x32_bf16 v[36:39], v[80:83], v[202:205], v[36:39]
	v_add_u32_e32 v80, 0x2180, v194
	s_or_b64 s[24:25], vcc, s[24:25]
	v_mfma_f32_16x16x32_bf16 v[76:79], v[84:87], v[198:201], v[76:79]
	v_mfma_f32_16x16x32_bf16 v[40:43], v[84:87], v[202:205], v[40:43]
	ds_read_b128 v[56:59], v195
	ds_read_b128 v[48:51], v195 offset:256
	ds_read_b64 v[86:87], v194 offset:8
	ds_read_b64 v[84:85], v194
	v_add_u32_e32 v194, 64, v194
	v_add_u32_e32 v195, 64, v195
	s_waitcnt lgkmcnt(5)
	v_mfma_f32_16x16x32_bf16 v[64:67], v[72:75], v[198:201], v[64:67]
	v_mfma_f32_16x16x32_bf16 v[44:47], v[72:75], v[202:205], v[44:47]
	s_waitcnt lgkmcnt(4)
	v_mfma_f32_16x16x32_bf16 v[60:63], v[52:55], v[198:201], v[60:63]
	ds_read_b64 v[82:83], v80 offset:8
	ds_read_b64 v[80:81], v80
	ds_read_b64 v[74:75], v196 offset:8
	ds_read_b64 v[72:73], v196
	ds_read_b64 v[200:201], v206 offset:8
	ds_read_b64 v[198:199], v206
	v_mfma_f32_16x16x32_bf16 v[32:35], v[52:55], v[202:205], v[32:35]
	s_waitcnt lgkmcnt(0)
	v_mov_b32_e32 v52, v198
	v_mov_b32_e32 v53, v199
	v_mov_b32_e32 v54, v200
	v_mov_b32_e32 v55, v201
	s_andn2_b64 exec, exec, s[24:25]
	s_cbranch_execnz .LBB0_647
	s_or_b64 exec, exec, s[24:25]

; template <int L>
; __device__ __forceinline__ void hy_conv(const bf16_t* F, const bf16_t* Bbuf, const bf16_t* Vbuf, bf16_t* Obuf, float skipv) {
;     ...
;         for (; d < dlast; d += 32) {
;             const bf16x8 b0n = *(const bf16x8*)(bp0 + d + 32), b1n = *(const bf16x8*)(bp1 + d + 32); bf16x8 an[4];
; #pragma unroll
;             for (int rho = 0; rho < 4; ++rho) an[rho] = HY_AFR(rho, d + 32);
; #pragma unroll
;             for (int rho = 0; rho < 4; ++rho) {
;                 acc0[rho] = __builtin_amdgcn_mfma_f32_16x16x32_bf16(ac[rho], b0c, acc0[rho], 0, 0, 0);
;                 acc1[rho] = __builtin_amdgcn_mfma_f32_16x16x32_bf16(ac[rho], b1c, acc1[rho], 0, 0, 0); }
;             b0c = b0n; b1c = b1n;
; #pragma unroll
;             for (int rho = 0; rho < 4; ++rho) ac[rho] = an[rho];
;         }
.LBB0_693:
	s_waitcnt lgkmcnt(5)
	v_mov_b64_e32 v[186:187], v[86:87]
	s_waitcnt lgkmcnt(4)
	v_mov_b64_e32 v[190:191], v[50:51]
	v_mov_b64_e32 v[184:185], v[84:85]
	v_mov_b64_e32 v[188:189], v[48:49]
	v_add_u32_e32 v84, 0xffffff00, v180
	s_waitcnt lgkmcnt(2)
	v_mfma_f32_16x16x32_bf16 v[68:71], v[76:79], v[184:187], v[68:71]
	v_add_u32_e32 v181, 0x4300, v161
	v_add_u32_e32 v183, 0x6480, v161
	v_add_u32_e32 v160, 32, v160
	v_mfma_f32_16x16x32_bf16 v[36:39], v[76:79], v[188:191], v[36:39]
	v_add_u32_e32 v76, 0x2180, v161
	v_cmp_ge_i32_e32 vcc, v160, v182
	s_or_b64 s[24:25], vcc, s[24:25]
	v_mfma_f32_16x16x32_bf16 v[72:75], v[80:83], v[184:187], v[72:75]
	v_mfma_f32_16x16x32_bf16 v[40:43], v[80:83], v[188:191], v[40:43]
	ds_read_b128 v[48:51], v180
	ds_read_b64 v[82:83], v161 offset:8
	ds_read_b64 v[80:81], v161
	ds_read_b128 v[84:87], v84
	v_add_u32_e32 v161, 64, v161
	s_waitcnt lgkmcnt(5)
	v_mfma_f32_16x16x32_bf16 v[60:63], v[64:67], v[184:187], v[60:63]
	v_add_u32_e32 v180, 64, v180
	v_mfma_f32_16x16x32_bf16 v[44:47], v[64:67], v[188:191], v[44:47]
	s_waitcnt lgkmcnt(4)
	v_mfma_f32_16x16x32_bf16 v[56:59], v[52:55], v[184:187], v[56:59]
	ds_read_b64 v[78:79], v76 offset:8
	ds_read_b64 v[76:77], v76
	ds_read_b64 v[66:67], v181 offset:8
	ds_read_b64 v[64:65], v181
	ds_read_b64 v[186:187], v183 offset:8
	ds_read_b64 v[184:185], v183
	v_mfma_f32_16x16x32_bf16 v[32:35], v[52:55], v[188:191], v[32:35]
	s_waitcnt lgkmcnt(0)
	v_mov_b32_e32 v52, v184
	v_mov_b32_e32 v53, v185
	v_mov_b32_e32 v54, v186
	v_mov_b32_e32 v55, v187
	s_andn2_b64 exec, exec, s[24:25]
	s_cbranch_execnz .LBB0_693
	s_or_b64 exec, exec, s[24:25]
